# GEMM K-loops: first 8 MFMAs of each 32-MFMA block issued before the pre-block barrier (operands already in registers)
# speedup vs baseline: 1.0001x; 1.0001x over previous
.LBB0_122:
	ds_read_b128 v[150:153], v146
	ds_read_b128 v[154:157], v146 offset:1024
	ds_read_b128 v[158:161], v146 offset:2048
	ds_read_b128 v[162:165], v146 offset:3072
	ds_read_b128 v[166:169], v147
	ds_read_b128 v[170:173], v147 offset:1024
	ds_read_b128 v[174:177], v147 offset:2048
	ds_read_b128 v[178:181], v147 offset:3072
	s_add_u32 s38, s36, 0xfffc0080
	s_addc_u32 s39, s37, -1
	s_cmp_eq_u32 s59, 12
	s_cselect_b32 s41, s1, s39
	s_cselect_b32 s40, s27, s38
	s_cselect_b32 s39, s25, s58
	s_cselect_b32 s38, s35, s57
	v_lshl_add_u64 v[142:143], s[36:37], 0, v[138:139]
	s_add_i32 m0, s44, 0xc000
	ds_read_b128 v[182:185], v148
	ds_read_b128 v[186:189], v148 offset:1024
	ds_read_b128 v[190:193], v148 offset:2048
	ds_read_b128 v[196:199], v148 offset:3072
	ds_read_b128 v[200:203], v148 offset:4096
	ds_read_b128 v[204:207], v148 offset:5120
	ds_read_b128 v[208:211], v148 offset:6144
	ds_read_b128 v[212:215], v148 offset:7168
	global_load_lds_dwordx4 v[142:143], off
	v_lshl_add_u64 v[142:143], s[36:37], 0, v[140:141]
	s_add_i32 m0, s44, 0xe000
	s_nop 0
	global_load_lds_dwordx4 v[142:143], off
	s_waitcnt lgkmcnt(0)
	v_mfma_f32_16x16x32_bf16 v[122:125], v[150:153], v[182:185], v[122:125]
	v_mfma_f32_16x16x32_bf16 v[126:129], v[158:161], v[182:185], v[126:129]
	v_mfma_f32_16x16x32_bf16 v[106:109], v[150:153], v[190:193], v[106:109]
	v_mfma_f32_16x16x32_bf16 v[110:113], v[158:161], v[190:193], v[110:113]
	v_mfma_f32_16x16x32_bf16 v[90:93], v[150:153], v[200:203], v[90:93]
	v_mfma_f32_16x16x32_bf16 v[94:97], v[158:161], v[200:203], v[94:97]
	v_mfma_f32_16x16x32_bf16 v[74:77], v[150:153], v[208:211], v[74:77]
	v_mfma_f32_16x16x32_bf16 v[78:81], v[158:161], v[208:211], v[78:81]
	s_waitcnt vmcnt(8)
	s_waitcnt lgkmcnt(0)
	s_barrier
	s_setprio 1
	s_waitcnt lgkmcnt(0)
	v_mfma_f32_16x16x32_bf16 v[122:125], v[154:157], v[186:189], v[122:125]
	v_mfma_f32_16x16x32_bf16 v[126:129], v[162:165], v[186:189], v[126:129]
	v_mfma_f32_16x16x32_bf16 v[106:109], v[154:157], v[196:199], v[106:109]
	v_mfma_f32_16x16x32_bf16 v[110:113], v[162:165], v[196:199], v[110:113]
	v_mfma_f32_16x16x32_bf16 v[90:93], v[154:157], v[204:207], v[90:93]
	v_mfma_f32_16x16x32_bf16 v[94:97], v[162:165], v[204:207], v[94:97]
	v_mfma_f32_16x16x32_bf16 v[74:77], v[154:157], v[212:215], v[74:77]
	v_mfma_f32_16x16x32_bf16 v[78:81], v[162:165], v[212:215], v[78:81]
	s_setprio 0
	s_setprio 1
	v_mfma_f32_16x16x32_bf16 v[118:121], v[166:169], v[182:185], v[118:121]
	v_mfma_f32_16x16x32_bf16 v[114:117], v[174:177], v[182:185], v[114:117]
	v_mfma_f32_16x16x32_bf16 v[102:105], v[166:169], v[190:193], v[102:105]
	v_mfma_f32_16x16x32_bf16 v[98:101], v[174:177], v[190:193], v[98:101]
	v_mfma_f32_16x16x32_bf16 v[86:89], v[166:169], v[200:203], v[86:89]
	v_mfma_f32_16x16x32_bf16 v[82:85], v[174:177], v[200:203], v[82:85]
	v_mfma_f32_16x16x32_bf16 v[70:73], v[166:169], v[208:211], v[70:73]
	v_mfma_f32_16x16x32_bf16 v[66:69], v[174:177], v[208:211], v[66:69]
	v_mfma_f32_16x16x32_bf16 v[118:121], v[170:173], v[186:189], v[118:121]
	v_mfma_f32_16x16x32_bf16 v[114:117], v[178:181], v[186:189], v[114:117]
	v_mfma_f32_16x16x32_bf16 v[102:105], v[170:173], v[196:199], v[102:105]
	v_mfma_f32_16x16x32_bf16 v[98:101], v[178:181], v[196:199], v[98:101]
	v_mfma_f32_16x16x32_bf16 v[86:89], v[170:173], v[204:207], v[86:89]
	v_mfma_f32_16x16x32_bf16 v[82:85], v[178:181], v[204:207], v[82:85]
	v_mfma_f32_16x16x32_bf16 v[70:73], v[170:173], v[212:215], v[70:73]
	v_mfma_f32_16x16x32_bf16 v[66:69], v[178:181], v[212:215], v[66:69]
	s_setprio 0
	s_barrier
	s_add_i32 s60, s53, s43
	v_lshl_add_u64 v[142:143], s[38:39], 0, v[132:133]
	s_mov_b32 m0, s60
	ds_read_b128 v[182:185], v148 offset:16384
	ds_read_b128 v[186:189], v148 offset:17408
	ds_read_b128 v[190:193], v148 offset:18432
	ds_read_b128 v[196:199], v148 offset:19456
	ds_read_b128 v[200:203], v148 offset:20480
	ds_read_b128 v[204:207], v148 offset:21504
	ds_read_b128 v[208:211], v148 offset:22528
	ds_read_b128 v[212:215], v148 offset:23552
	global_load_lds_dwordx4 v[142:143], off
	s_add_i32 m0, s60, 0x2000
	s_add_u32 s60, s38, 0x40000
	v_lshl_add_u64 v[216:217], s[38:39], 0, v[136:137]
	s_addc_u32 s61, s39, 0
	s_add_i32 s62, s54, s43
	global_load_lds_dwordx4 v[216:217], off
	v_lshl_add_u64 v[218:219], s[60:61], 0, v[132:133]
	s_mov_b32 m0, s62
	v_lshl_add_u64 v[220:221], s[40:41], 0, v[134:135]
	global_load_lds_dwordx4 v[218:219], off
	v_lshl_add_u64 v[218:219], s[60:61], 0, v[136:137]
	s_add_i32 m0, s62, 0x2000
	s_nop 0
	global_load_lds_dwordx4 v[218:219], off
	v_lshl_add_u64 v[218:219], s[40:41], 0, v[130:131]
	s_mov_b32 m0, s44
	s_nop 0
	global_load_lds_dwordx4 v[218:219], off
	s_mov_b32 m0, s45
	s_nop 0
	global_load_lds_dwordx4 v[220:221], off
	s_waitcnt lgkmcnt(0)
	v_mfma_f32_16x16x32_bf16 v[58:61], v[150:153], v[182:185], v[58:61]
	v_mfma_f32_16x16x32_bf16 v[62:65], v[158:161], v[182:185], v[62:65]
	v_mfma_f32_16x16x32_bf16 v[42:45], v[150:153], v[190:193], v[42:45]
	v_mfma_f32_16x16x32_bf16 v[46:49], v[158:161], v[190:193], v[46:49]
	v_mfma_f32_16x16x32_bf16 v[26:29], v[150:153], v[200:203], v[26:29]
	v_mfma_f32_16x16x32_bf16 v[30:33], v[158:161], v[200:203], v[30:33]
	v_mfma_f32_16x16x32_bf16 v[10:13], v[150:153], v[208:211], v[10:13]
	v_mfma_f32_16x16x32_bf16 v[14:17], v[158:161], v[208:211], v[14:17]
	s_waitcnt vmcnt(8)
	s_waitcnt lgkmcnt(0)
	s_barrier
	s_setprio 1
	s_waitcnt lgkmcnt(0)
	v_mfma_f32_16x16x32_bf16 v[58:61], v[154:157], v[186:189], v[58:61]
	v_mfma_f32_16x16x32_bf16 v[62:65], v[162:165], v[186:189], v[62:65]
	v_mfma_f32_16x16x32_bf16 v[42:45], v[154:157], v[196:199], v[42:45]
	v_mfma_f32_16x16x32_bf16 v[46:49], v[162:165], v[196:199], v[46:49]
	v_mfma_f32_16x16x32_bf16 v[26:29], v[154:157], v[204:207], v[26:29]
	v_mfma_f32_16x16x32_bf16 v[30:33], v[162:165], v[204:207], v[30:33]
	v_mfma_f32_16x16x32_bf16 v[10:13], v[154:157], v[212:215], v[10:13]
	v_mfma_f32_16x16x32_bf16 v[14:17], v[162:165], v[212:215], v[14:17]
	s_setprio 0
	s_setprio 1
	v_mfma_f32_16x16x32_bf16 v[54:57], v[166:169], v[182:185], v[54:57]
	v_mfma_f32_16x16x32_bf16 v[50:53], v[174:177], v[182:185], v[50:53]
	v_mfma_f32_16x16x32_bf16 v[38:41], v[166:169], v[190:193], v[38:41]
	v_mfma_f32_16x16x32_bf16 v[34:37], v[174:177], v[190:193], v[34:37]
	v_mfma_f32_16x16x32_bf16 v[22:25], v[166:169], v[200:203], v[22:25]
	v_mfma_f32_16x16x32_bf16 v[18:21], v[174:177], v[200:203], v[18:21]
	v_mfma_f32_16x16x32_bf16 v[6:9], v[166:169], v[208:211], v[6:9]
	v_mfma_f32_16x16x32_bf16 v[2:5], v[174:177], v[208:211], v[2:5]
	v_mfma_f32_16x16x32_bf16 v[54:57], v[170:173], v[186:189], v[54:57]
	v_mfma_f32_16x16x32_bf16 v[50:53], v[178:181], v[186:189], v[50:53]
	v_mfma_f32_16x16x32_bf16 v[38:41], v[170:173], v[196:199], v[38:41]
	v_mfma_f32_16x16x32_bf16 v[34:37], v[178:181], v[196:199], v[34:37]
	v_mfma_f32_16x16x32_bf16 v[22:25], v[170:173], v[204:207], v[22:25]
	v_mfma_f32_16x16x32_bf16 v[18:21], v[178:181], v[204:207], v[18:21]
	v_mfma_f32_16x16x32_bf16 v[6:9], v[170:173], v[212:215], v[6:9]
	v_mfma_f32_16x16x32_bf16 v[2:5], v[178:181], v[212:215], v[2:5]
	s_setprio 0
	s_barrier
	s_add_i32 s60, 0, 0x18000
	v_add_u32_e32 v149, s60, v144
	s_add_i32 s61, 0, 0x1c000
	ds_read_b128 v[150:153], v149
	ds_read_b128 v[154:157], v149 offset:1024
	ds_read_b128 v[158:161], v149 offset:2048
	ds_read_b128 v[162:165], v149 offset:3072
	v_add_u32_e32 v149, s61, v144
	ds_read_b128 v[166:169], v149
	ds_read_b128 v[170:173], v149 offset:1024
	ds_read_b128 v[174:177], v149 offset:2048
	ds_read_b128 v[178:181], v149 offset:3072
	s_add_u32 s40, s40, 0x40000
	s_addc_u32 s41, s41, 0
	s_mov_b32 m0, s46
	v_lshl_add_u64 v[222:223], s[40:41], 0, v[130:131]
	ds_read_b128 v[182:185], v148 offset:32768
	ds_read_b128 v[186:189], v148 offset:33792
	ds_read_b128 v[190:193], v148 offset:34816
	ds_read_b128 v[196:199], v148 offset:35840
	ds_read_b128 v[200:203], v148 offset:36864
	ds_read_b128 v[204:207], v148 offset:37888
	ds_read_b128 v[208:211], v148 offset:38912
	ds_read_b128 v[212:215], v148 offset:39936
	global_load_lds_dwordx4 v[222:223], off
	v_lshl_add_u64 v[222:223], s[40:41], 0, v[134:135]
	s_mov_b32 m0, s47
	s_nop 0
	global_load_lds_dwordx4 v[222:223], off
	s_waitcnt lgkmcnt(0)
	v_mfma_f32_16x16x32_bf16 v[122:125], v[150:153], v[182:185], v[122:125]
	v_mfma_f32_16x16x32_bf16 v[126:129], v[158:161], v[182:185], v[126:129]
	v_mfma_f32_16x16x32_bf16 v[106:109], v[150:153], v[190:193], v[106:109]
	v_mfma_f32_16x16x32_bf16 v[110:113], v[158:161], v[190:193], v[110:113]
	v_mfma_f32_16x16x32_bf16 v[90:93], v[150:153], v[200:203], v[90:93]
	v_mfma_f32_16x16x32_bf16 v[94:97], v[158:161], v[200:203], v[94:97]
	v_mfma_f32_16x16x32_bf16 v[74:77], v[150:153], v[208:211], v[74:77]
	v_mfma_f32_16x16x32_bf16 v[78:81], v[158:161], v[208:211], v[78:81]
	s_waitcnt vmcnt(8)
	s_waitcnt lgkmcnt(0)
	s_barrier
	s_setprio 1
	s_waitcnt lgkmcnt(0)
	v_mfma_f32_16x16x32_bf16 v[122:125], v[154:157], v[186:189], v[122:125]
	v_mfma_f32_16x16x32_bf16 v[126:129], v[162:165], v[186:189], v[126:129]
	v_mfma_f32_16x16x32_bf16 v[106:109], v[154:157], v[196:199], v[106:109]
	v_mfma_f32_16x16x32_bf16 v[110:113], v[162:165], v[196:199], v[110:113]
	v_mfma_f32_16x16x32_bf16 v[90:93], v[154:157], v[204:207], v[90:93]
	v_mfma_f32_16x16x32_bf16 v[94:97], v[162:165], v[204:207], v[94:97]
	v_mfma_f32_16x16x32_bf16 v[74:77], v[154:157], v[212:215], v[74:77]
	v_mfma_f32_16x16x32_bf16 v[78:81], v[162:165], v[212:215], v[78:81]
	s_setprio 0
	s_setprio 1
	v_mfma_f32_16x16x32_bf16 v[118:121], v[166:169], v[182:185], v[118:121]
	v_mfma_f32_16x16x32_bf16 v[114:117], v[174:177], v[182:185], v[114:117]
	v_mfma_f32_16x16x32_bf16 v[102:105], v[166:169], v[190:193], v[102:105]
	v_mfma_f32_16x16x32_bf16 v[98:101], v[174:177], v[190:193], v[98:101]
	v_mfma_f32_16x16x32_bf16 v[86:89], v[166:169], v[200:203], v[86:89]
	v_mfma_f32_16x16x32_bf16 v[82:85], v[174:177], v[200:203], v[82:85]
	v_mfma_f32_16x16x32_bf16 v[70:73], v[166:169], v[208:211], v[70:73]
	v_mfma_f32_16x16x32_bf16 v[66:69], v[174:177], v[208:211], v[66:69]
	v_mfma_f32_16x16x32_bf16 v[118:121], v[170:173], v[186:189], v[118:121]
	v_mfma_f32_16x16x32_bf16 v[114:117], v[178:181], v[186:189], v[114:117]
	v_mfma_f32_16x16x32_bf16 v[102:105], v[170:173], v[196:199], v[102:105]
	v_mfma_f32_16x16x32_bf16 v[98:101], v[178:181], v[196:199], v[98:101]
	v_mfma_f32_16x16x32_bf16 v[86:89], v[170:173], v[204:207], v[86:89]
	v_mfma_f32_16x16x32_bf16 v[82:85], v[178:181], v[204:207], v[82:85]
	v_mfma_f32_16x16x32_bf16 v[70:73], v[170:173], v[212:215], v[70:73]
	v_mfma_f32_16x16x32_bf16 v[66:69], v[178:181], v[212:215], v[66:69]
	s_setprio 0
	s_barrier
	s_add_i32 s40, s60, s43
	v_lshl_add_u64 v[142:143], v[142:143], 0, s[12:13]
	s_mov_b32 m0, s40
	ds_read_b128 v[182:185], v148 offset:49152
	ds_read_b128 v[186:189], v148 offset:50176
	ds_read_b128 v[190:193], v148 offset:51200
	ds_read_b128 v[196:199], v148 offset:52224
	ds_read_b128 v[200:203], v148 offset:53248
	ds_read_b128 v[204:207], v148 offset:54272
	ds_read_b128 v[208:211], v148 offset:55296
	ds_read_b128 v[212:215], v148 offset:56320
	global_load_lds_dwordx4 v[142:143], off
	s_add_i32 m0, s40, 0x2000
	s_add_u32 s38, s38, 0x40080
	v_lshl_add_u64 v[142:143], v[216:217], 0, s[12:13]
	s_addc_u32 s39, s39, 0
	s_add_i32 s40, s61, s43
	global_load_lds_dwordx4 v[142:143], off
	v_lshl_add_u64 v[142:143], s[38:39], 0, v[132:133]
	s_mov_b32 m0, s40
	s_nop 0
	global_load_lds_dwordx4 v[142:143], off
	v_lshl_add_u64 v[142:143], s[38:39], 0, v[136:137]
	s_add_i32 m0, s40, 0x2000
	s_nop 0
	global_load_lds_dwordx4 v[142:143], off
	v_lshl_add_u64 v[142:143], v[218:219], 0, s[12:13]
	s_mov_b32 m0, s49
	s_nop 0
	global_load_lds_dwordx4 v[142:143], off
	v_lshl_add_u64 v[142:143], v[220:221], 0, s[12:13]
	s_mov_b32 m0, s50
	s_nop 0
	global_load_lds_dwordx4 v[142:143], off
	s_waitcnt lgkmcnt(0)
	v_mfma_f32_16x16x32_bf16 v[58:61], v[150:153], v[182:185], v[58:61]
	v_mfma_f32_16x16x32_bf16 v[62:65], v[158:161], v[182:185], v[62:65]
	v_mfma_f32_16x16x32_bf16 v[42:45], v[150:153], v[190:193], v[42:45]
	v_mfma_f32_16x16x32_bf16 v[46:49], v[158:161], v[190:193], v[46:49]
	v_mfma_f32_16x16x32_bf16 v[26:29], v[150:153], v[200:203], v[26:29]
	v_mfma_f32_16x16x32_bf16 v[30:33], v[158:161], v[200:203], v[30:33]
	v_mfma_f32_16x16x32_bf16 v[10:13], v[150:153], v[208:211], v[10:13]
	v_mfma_f32_16x16x32_bf16 v[14:17], v[158:161], v[208:211], v[14:17]
	s_waitcnt vmcnt(8)
	s_waitcnt lgkmcnt(0)
	s_barrier
	s_setprio 1
	s_waitcnt lgkmcnt(0)
	v_mfma_f32_16x16x32_bf16 v[58:61], v[154:157], v[186:189], v[58:61]
	v_mfma_f32_16x16x32_bf16 v[62:65], v[162:165], v[186:189], v[62:65]
	v_mfma_f32_16x16x32_bf16 v[42:45], v[154:157], v[196:199], v[42:45]
	v_mfma_f32_16x16x32_bf16 v[46:49], v[162:165], v[196:199], v[46:49]
	v_mfma_f32_16x16x32_bf16 v[26:29], v[154:157], v[204:207], v[26:29]
	v_mfma_f32_16x16x32_bf16 v[30:33], v[162:165], v[204:207], v[30:33]
	v_mfma_f32_16x16x32_bf16 v[10:13], v[154:157], v[212:215], v[10:13]
	v_mfma_f32_16x16x32_bf16 v[14:17], v[162:165], v[212:215], v[14:17]
	s_setprio 0
	s_setprio 1
	v_mfma_f32_16x16x32_bf16 v[54:57], v[166:169], v[182:185], v[54:57]
	v_mfma_f32_16x16x32_bf16 v[50:53], v[174:177], v[182:185], v[50:53]
	v_mfma_f32_16x16x32_bf16 v[38:41], v[166:169], v[190:193], v[38:41]
	v_mfma_f32_16x16x32_bf16 v[34:37], v[174:177], v[190:193], v[34:37]
	v_mfma_f32_16x16x32_bf16 v[22:25], v[166:169], v[200:203], v[22:25]
	v_mfma_f32_16x16x32_bf16 v[18:21], v[174:177], v[200:203], v[18:21]
	v_mfma_f32_16x16x32_bf16 v[6:9], v[166:169], v[208:211], v[6:9]
	v_mfma_f32_16x16x32_bf16 v[2:5], v[174:177], v[208:211], v[2:5]
	v_mfma_f32_16x16x32_bf16 v[54:57], v[170:173], v[186:189], v[54:57]
	v_mfma_f32_16x16x32_bf16 v[50:53], v[178:181], v[186:189], v[50:53]
	v_mfma_f32_16x16x32_bf16 v[38:41], v[170:173], v[196:199], v[38:41]
	v_mfma_f32_16x16x32_bf16 v[34:37], v[178:181], v[196:199], v[34:37]
	v_mfma_f32_16x16x32_bf16 v[22:25], v[170:173], v[204:207], v[22:25]
	v_mfma_f32_16x16x32_bf16 v[18:21], v[178:181], v[204:207], v[18:21]
	v_mfma_f32_16x16x32_bf16 v[6:9], v[170:173], v[212:215], v[6:9]
	v_mfma_f32_16x16x32_bf16 v[2:5], v[178:181], v[212:215], v[2:5]
	s_setprio 0
	s_barrier
	s_add_i32 s59, s59, 2
	s_add_u32 s36, s36, 0x100
	s_addc_u32 s37, s37, 0
	s_add_u32 s57, s57, 0x100
	s_addc_u32 s58, s58, 0
	s_cmp_gt_u32 s59, 13
	s_cbranch_scc0 .LBB0_122
	s_and_b64 vcc, exec, s[14:15]
	s_cbranch_vccz .LBB0_125
	s_barrier

.LBB0_581:
	s_add_u32 s22, s18, s20
	s_addc_u32 s23, s19, s21
	s_add_u32 s22, s22, 0x100
	s_addc_u32 s23, s23, 0
	s_add_u32 s47, s44, s20
	s_addc_u32 s48, s45, s21
	s_cmpk_eq_i32 s20, 0x700
	v_add_u32_e32 v142, s39, v185
	v_add_u32_e32 v159, s40, v185
	ds_read_b128 v[130:133], v142
	ds_read_b128 v[134:137], v142 offset:1024
	ds_read_b128 v[138:141], v142 offset:2048
	ds_read_b128 v[142:145], v142 offset:3072
	ds_read_b128 v[146:149], v159
	ds_read_b128 v[150:153], v159 offset:1024
	ds_read_b128 v[154:157], v159 offset:2048
	ds_read_b128 v[178:181], v159 offset:3072
	s_cselect_b32 s25, s11, s23
	s_cselect_b32 s24, s42, s22
	s_cselect_b32 s23, s9, s48
	s_cselect_b32 s22, s43, s47
	v_lshl_add_u64 v[182:183], v[174:175], 0, s[20:21]
	s_add_i32 m0, s28, 0xc000
	ds_read_b128 v[190:193], v188
	ds_read_b128 v[196:199], v188 offset:1024
	ds_read_b128 v[200:203], v188 offset:2048
	ds_read_b128 v[204:207], v188 offset:3072
	ds_read_b128 v[208:211], v188 offset:4096
	ds_read_b128 v[212:215], v188 offset:5120
	ds_read_b128 v[216:219], v188 offset:6144
	ds_read_b128 v[220:223], v188 offset:7168
	global_load_lds_dwordx4 v[182:183], off
	v_lshl_add_u64 v[182:183], v[176:177], 0, s[20:21]
	s_add_i32 m0, s28, 0xe000
	s_nop 0
	global_load_lds_dwordx4 v[182:183], off
	s_waitcnt lgkmcnt(0)
	v_mfma_f32_16x16x32_bf16 v[126:129], v[130:133], v[190:193], v[126:129]
	v_mfma_f32_16x16x32_bf16 v[122:125], v[138:141], v[190:193], v[122:125]
	v_mfma_f32_16x16x32_bf16 v[114:117], v[130:133], v[200:203], v[114:117]
	v_mfma_f32_16x16x32_bf16 v[106:109], v[138:141], v[200:203], v[106:109]
	v_mfma_f32_16x16x32_bf16 v[98:101], v[130:133], v[208:211], v[98:101]
	v_mfma_f32_16x16x32_bf16 v[90:93], v[138:141], v[208:211], v[90:93]
	v_mfma_f32_16x16x32_bf16 v[82:85], v[130:133], v[216:219], v[82:85]
	v_mfma_f32_16x16x32_bf16 v[74:77], v[138:141], v[216:219], v[74:77]
	s_waitcnt vmcnt(8)
	s_waitcnt lgkmcnt(0)
	s_barrier
	s_setprio 1
	s_waitcnt lgkmcnt(0)
	v_mfma_f32_16x16x32_bf16 v[126:129], v[134:137], v[196:199], v[126:129]
	v_mfma_f32_16x16x32_bf16 v[122:125], v[142:145], v[196:199], v[122:125]
	v_mfma_f32_16x16x32_bf16 v[114:117], v[134:137], v[204:207], v[114:117]
	v_mfma_f32_16x16x32_bf16 v[106:109], v[142:145], v[204:207], v[106:109]
	v_mfma_f32_16x16x32_bf16 v[98:101], v[134:137], v[212:215], v[98:101]
	v_mfma_f32_16x16x32_bf16 v[90:93], v[142:145], v[212:215], v[90:93]
	v_mfma_f32_16x16x32_bf16 v[82:85], v[134:137], v[220:223], v[82:85]
	v_mfma_f32_16x16x32_bf16 v[74:77], v[142:145], v[220:223], v[74:77]
	s_setprio 0
	s_setprio 1
	v_mfma_f32_16x16x32_bf16 v[118:121], v[146:149], v[190:193], v[118:121]
	v_mfma_f32_16x16x32_bf16 v[110:113], v[154:157], v[190:193], v[110:113]
	v_mfma_f32_16x16x32_bf16 v[102:105], v[146:149], v[200:203], v[102:105]
	v_mfma_f32_16x16x32_bf16 v[94:97], v[154:157], v[200:203], v[94:97]
	v_mfma_f32_16x16x32_bf16 v[86:89], v[146:149], v[208:211], v[86:89]
	v_mfma_f32_16x16x32_bf16 v[78:81], v[154:157], v[208:211], v[78:81]
	v_mfma_f32_16x16x32_bf16 v[70:73], v[146:149], v[216:219], v[70:73]
	v_mfma_f32_16x16x32_bf16 v[66:69], v[154:157], v[216:219], v[66:69]
	v_mfma_f32_16x16x32_bf16 v[118:121], v[150:153], v[196:199], v[118:121]
	v_mfma_f32_16x16x32_bf16 v[110:113], v[178:181], v[196:199], v[110:113]
	v_mfma_f32_16x16x32_bf16 v[102:105], v[150:153], v[204:207], v[102:105]
	v_mfma_f32_16x16x32_bf16 v[94:97], v[178:181], v[204:207], v[94:97]
	v_mfma_f32_16x16x32_bf16 v[86:89], v[150:153], v[212:215], v[86:89]
	v_mfma_f32_16x16x32_bf16 v[78:81], v[178:181], v[212:215], v[78:81]
	v_mfma_f32_16x16x32_bf16 v[70:73], v[150:153], v[220:223], v[70:73]
	v_mfma_f32_16x16x32_bf16 v[66:69], v[178:181], v[220:223], v[66:69]
	s_setprio 0
	s_barrier
	s_add_i32 s47, s39, s27
	v_lshl_add_u64 v[182:183], s[22:23], 0, v[164:165]
	s_mov_b32 m0, s47
	ds_read_b128 v[190:193], v188 offset:16384
	ds_read_b128 v[196:199], v188 offset:17408
	ds_read_b128 v[200:203], v188 offset:18432
	ds_read_b128 v[204:207], v188 offset:19456
	ds_read_b128 v[208:211], v188 offset:20480
	ds_read_b128 v[212:215], v188 offset:21504
	ds_read_b128 v[216:219], v188 offset:22528
	ds_read_b128 v[220:223], v188 offset:23552
	global_load_lds_dwordx4 v[182:183], off
	s_add_i32 m0, s47, 0x2000
	s_add_u32 s48, s22, 0x40000
	v_lshl_add_u64 v[224:225], s[22:23], 0, v[168:169]
	s_addc_u32 s49, s23, 0
	s_add_i32 s47, s40, s27
	global_load_lds_dwordx4 v[224:225], off
	v_lshl_add_u64 v[226:227], s[48:49], 0, v[164:165]
	s_mov_b32 m0, s47
	v_lshl_add_u64 v[228:229], s[24:25], 0, v[166:167]
	global_load_lds_dwordx4 v[226:227], off
	v_lshl_add_u64 v[226:227], s[48:49], 0, v[168:169]
	s_add_i32 m0, s47, 0x2000
	s_nop 0
	global_load_lds_dwordx4 v[226:227], off
	v_lshl_add_u64 v[226:227], s[24:25], 0, v[162:163]
	s_mov_b32 m0, s28
	s_nop 0
	global_load_lds_dwordx4 v[226:227], off
	s_mov_b32 m0, s29
	s_nop 0
	global_load_lds_dwordx4 v[228:229], off
	s_waitcnt lgkmcnt(0)
	v_mfma_f32_16x16x32_bf16 v[62:65], v[130:133], v[190:193], v[62:65]
	v_mfma_f32_16x16x32_bf16 v[58:61], v[138:141], v[190:193], v[58:61]
	v_mfma_f32_16x16x32_bf16 v[50:53], v[130:133], v[200:203], v[50:53]
	v_mfma_f32_16x16x32_bf16 v[42:45], v[138:141], v[200:203], v[42:45]
	v_mfma_f32_16x16x32_bf16 v[34:37], v[130:133], v[208:211], v[34:37]
	v_mfma_f32_16x16x32_bf16 v[26:29], v[138:141], v[208:211], v[26:29]
	v_mfma_f32_16x16x32_bf16 v[18:21], v[130:133], v[216:219], v[18:21]
	v_mfma_f32_16x16x32_bf16 v[10:13], v[138:141], v[216:219], v[10:13]
	s_waitcnt vmcnt(8)
	s_waitcnt lgkmcnt(0)
	s_barrier
	s_setprio 1
	s_waitcnt lgkmcnt(0)
	v_mfma_f32_16x16x32_bf16 v[62:65], v[134:137], v[196:199], v[62:65]
	v_mfma_f32_16x16x32_bf16 v[58:61], v[142:145], v[196:199], v[58:61]
	v_mfma_f32_16x16x32_bf16 v[50:53], v[134:137], v[204:207], v[50:53]
	v_mfma_f32_16x16x32_bf16 v[42:45], v[142:145], v[204:207], v[42:45]
	v_mfma_f32_16x16x32_bf16 v[34:37], v[134:137], v[212:215], v[34:37]
	v_mfma_f32_16x16x32_bf16 v[26:29], v[142:145], v[212:215], v[26:29]
	v_mfma_f32_16x16x32_bf16 v[18:21], v[134:137], v[220:223], v[18:21]
	v_mfma_f32_16x16x32_bf16 v[10:13], v[142:145], v[220:223], v[10:13]
	s_setprio 0
	s_setprio 1
	v_mfma_f32_16x16x32_bf16 v[54:57], v[146:149], v[190:193], v[54:57]
	v_mfma_f32_16x16x32_bf16 v[46:49], v[154:157], v[190:193], v[46:49]
	v_mfma_f32_16x16x32_bf16 v[38:41], v[146:149], v[200:203], v[38:41]
	v_mfma_f32_16x16x32_bf16 v[30:33], v[154:157], v[200:203], v[30:33]
	v_mfma_f32_16x16x32_bf16 v[22:25], v[146:149], v[208:211], v[22:25]
	v_mfma_f32_16x16x32_bf16 v[14:17], v[154:157], v[208:211], v[14:17]
	v_mfma_f32_16x16x32_bf16 v[6:9], v[146:149], v[216:219], v[6:9]
	v_mfma_f32_16x16x32_bf16 v[2:5], v[154:157], v[216:219], v[2:5]
	v_mfma_f32_16x16x32_bf16 v[54:57], v[150:153], v[196:199], v[54:57]
	v_mfma_f32_16x16x32_bf16 v[46:49], v[178:181], v[196:199], v[46:49]
	v_mfma_f32_16x16x32_bf16 v[38:41], v[150:153], v[204:207], v[38:41]
	v_mfma_f32_16x16x32_bf16 v[30:33], v[178:181], v[204:207], v[30:33]
	v_mfma_f32_16x16x32_bf16 v[22:25], v[150:153], v[212:215], v[22:25]
	v_mfma_f32_16x16x32_bf16 v[14:17], v[178:181], v[212:215], v[14:17]
	v_mfma_f32_16x16x32_bf16 v[6:9], v[150:153], v[220:223], v[6:9]
	v_mfma_f32_16x16x32_bf16 v[2:5], v[178:181], v[220:223], v[2:5]
	s_setprio 0
	s_barrier
	s_add_i32 s47, 0, 0x18000
	s_add_i32 s48, 0, 0x1c000
	v_add_u32_e32 v142, s47, v185
	v_add_u32_e32 v159, s48, v185
	ds_read_b128 v[130:133], v142
	ds_read_b128 v[134:137], v142 offset:1024
	ds_read_b128 v[138:141], v142 offset:2048
	ds_read_b128 v[142:145], v142 offset:3072
	ds_read_b128 v[146:149], v159
	ds_read_b128 v[150:153], v159 offset:1024
	ds_read_b128 v[154:157], v159 offset:2048
	ds_read_b128 v[178:181], v159 offset:3072
	s_add_u32 s24, s24, 0x40000
	s_addc_u32 s25, s25, 0
	s_mov_b32 m0, s30
	v_lshl_add_u64 v[230:231], s[24:25], 0, v[162:163]
	ds_read_b128 v[190:193], v188 offset:32768
	ds_read_b128 v[196:199], v188 offset:33792
	ds_read_b128 v[200:203], v188 offset:34816
	ds_read_b128 v[204:207], v188 offset:35840
	ds_read_b128 v[208:211], v188 offset:36864
	ds_read_b128 v[212:215], v188 offset:37888
	ds_read_b128 v[216:219], v188 offset:38912
	ds_read_b128 v[220:223], v188 offset:39936
	global_load_lds_dwordx4 v[230:231], off
	v_lshl_add_u64 v[230:231], s[24:25], 0, v[166:167]
	s_mov_b32 m0, s31
	s_nop 0
	global_load_lds_dwordx4 v[230:231], off
	s_waitcnt lgkmcnt(0)
	v_mfma_f32_16x16x32_bf16 v[126:129], v[130:133], v[190:193], v[126:129]
	v_mfma_f32_16x16x32_bf16 v[122:125], v[138:141], v[190:193], v[122:125]
	v_mfma_f32_16x16x32_bf16 v[114:117], v[130:133], v[200:203], v[114:117]
	v_mfma_f32_16x16x32_bf16 v[106:109], v[138:141], v[200:203], v[106:109]
	v_mfma_f32_16x16x32_bf16 v[98:101], v[130:133], v[208:211], v[98:101]
	v_mfma_f32_16x16x32_bf16 v[90:93], v[138:141], v[208:211], v[90:93]
	v_mfma_f32_16x16x32_bf16 v[82:85], v[130:133], v[216:219], v[82:85]
	v_mfma_f32_16x16x32_bf16 v[74:77], v[138:141], v[216:219], v[74:77]
	s_waitcnt vmcnt(8)
	s_waitcnt lgkmcnt(0)
	s_barrier
	s_setprio 1
	s_waitcnt lgkmcnt(0)
	v_mfma_f32_16x16x32_bf16 v[126:129], v[134:137], v[196:199], v[126:129]
	v_mfma_f32_16x16x32_bf16 v[122:125], v[142:145], v[196:199], v[122:125]
	v_mfma_f32_16x16x32_bf16 v[114:117], v[134:137], v[204:207], v[114:117]
	v_mfma_f32_16x16x32_bf16 v[106:109], v[142:145], v[204:207], v[106:109]
	v_mfma_f32_16x16x32_bf16 v[98:101], v[134:137], v[212:215], v[98:101]
	v_mfma_f32_16x16x32_bf16 v[90:93], v[142:145], v[212:215], v[90:93]
	v_mfma_f32_16x16x32_bf16 v[82:85], v[134:137], v[220:223], v[82:85]
	v_mfma_f32_16x16x32_bf16 v[74:77], v[142:145], v[220:223], v[74:77]
	s_setprio 0
	s_setprio 1
	v_mfma_f32_16x16x32_bf16 v[118:121], v[146:149], v[190:193], v[118:121]
	v_mfma_f32_16x16x32_bf16 v[110:113], v[154:157], v[190:193], v[110:113]
	v_mfma_f32_16x16x32_bf16 v[102:105], v[146:149], v[200:203], v[102:105]
	v_mfma_f32_16x16x32_bf16 v[94:97], v[154:157], v[200:203], v[94:97]
	v_mfma_f32_16x16x32_bf16 v[86:89], v[146:149], v[208:211], v[86:89]
	v_mfma_f32_16x16x32_bf16 v[78:81], v[154:157], v[208:211], v[78:81]
	v_mfma_f32_16x16x32_bf16 v[70:73], v[146:149], v[216:219], v[70:73]
	v_mfma_f32_16x16x32_bf16 v[66:69], v[154:157], v[216:219], v[66:69]
	v_mfma_f32_16x16x32_bf16 v[118:121], v[150:153], v[196:199], v[118:121]
	v_mfma_f32_16x16x32_bf16 v[110:113], v[178:181], v[196:199], v[110:113]
	v_mfma_f32_16x16x32_bf16 v[102:105], v[150:153], v[204:207], v[102:105]
	v_mfma_f32_16x16x32_bf16 v[94:97], v[178:181], v[204:207], v[94:97]
	v_mfma_f32_16x16x32_bf16 v[86:89], v[150:153], v[212:215], v[86:89]
	v_mfma_f32_16x16x32_bf16 v[78:81], v[178:181], v[212:215], v[78:81]
	v_mfma_f32_16x16x32_bf16 v[70:73], v[150:153], v[220:223], v[70:73]
	v_mfma_f32_16x16x32_bf16 v[66:69], v[178:181], v[220:223], v[66:69]
	s_setprio 0
	s_barrier
	s_add_i32 s24, s47, s27
	v_lshl_add_u64 v[182:183], v[182:183], 0, s[4:5]
	s_mov_b32 m0, s24
	ds_read_b128 v[190:193], v188 offset:49152
	ds_read_b128 v[196:199], v188 offset:50176
	ds_read_b128 v[200:203], v188 offset:51200
	ds_read_b128 v[204:207], v188 offset:52224
	ds_read_b128 v[208:211], v188 offset:53248
	ds_read_b128 v[212:215], v188 offset:54272
	ds_read_b128 v[216:219], v188 offset:55296
	ds_read_b128 v[220:223], v188 offset:56320
	global_load_lds_dwordx4 v[182:183], off
	s_add_i32 m0, s24, 0x2000
	s_add_u32 s22, s22, 0x40080
	v_lshl_add_u64 v[182:183], v[224:225], 0, s[4:5]
	s_addc_u32 s23, s23, 0
	s_add_i32 s24, s48, s27
	global_load_lds_dwordx4 v[182:183], off
	v_lshl_add_u64 v[182:183], s[22:23], 0, v[164:165]
	s_mov_b32 m0, s24
	s_nop 0
	global_load_lds_dwordx4 v[182:183], off
	v_lshl_add_u64 v[182:183], s[22:23], 0, v[168:169]
	s_add_i32 m0, s24, 0x2000
	s_nop 0
	global_load_lds_dwordx4 v[182:183], off
	v_lshl_add_u64 v[182:183], v[226:227], 0, s[4:5]
	s_mov_b32 m0, s34
	s_nop 0
	global_load_lds_dwordx4 v[182:183], off
	v_lshl_add_u64 v[182:183], v[228:229], 0, s[4:5]
	s_mov_b32 m0, s35
	s_nop 0
	global_load_lds_dwordx4 v[182:183], off
	s_waitcnt lgkmcnt(0)
	v_mfma_f32_16x16x32_bf16 v[62:65], v[130:133], v[190:193], v[62:65]
	v_mfma_f32_16x16x32_bf16 v[58:61], v[138:141], v[190:193], v[58:61]
	v_mfma_f32_16x16x32_bf16 v[50:53], v[130:133], v[200:203], v[50:53]
	v_mfma_f32_16x16x32_bf16 v[42:45], v[138:141], v[200:203], v[42:45]
	v_mfma_f32_16x16x32_bf16 v[34:37], v[130:133], v[208:211], v[34:37]
	v_mfma_f32_16x16x32_bf16 v[26:29], v[138:141], v[208:211], v[26:29]
	v_mfma_f32_16x16x32_bf16 v[18:21], v[130:133], v[216:219], v[18:21]
	v_mfma_f32_16x16x32_bf16 v[10:13], v[138:141], v[216:219], v[10:13]
	s_waitcnt vmcnt(8)
	s_waitcnt lgkmcnt(0)
	s_barrier
	s_setprio 1
	s_waitcnt lgkmcnt(0)
	v_mfma_f32_16x16x32_bf16 v[62:65], v[134:137], v[196:199], v[62:65]
	v_mfma_f32_16x16x32_bf16 v[58:61], v[142:145], v[196:199], v[58:61]
	v_mfma_f32_16x16x32_bf16 v[50:53], v[134:137], v[204:207], v[50:53]
	v_mfma_f32_16x16x32_bf16 v[42:45], v[142:145], v[204:207], v[42:45]
	v_mfma_f32_16x16x32_bf16 v[34:37], v[134:137], v[212:215], v[34:37]
	v_mfma_f32_16x16x32_bf16 v[26:29], v[142:145], v[212:215], v[26:29]
	v_mfma_f32_16x16x32_bf16 v[18:21], v[134:137], v[220:223], v[18:21]
	v_mfma_f32_16x16x32_bf16 v[10:13], v[142:145], v[220:223], v[10:13]
	s_setprio 0
	s_setprio 1
	v_mfma_f32_16x16x32_bf16 v[54:57], v[146:149], v[190:193], v[54:57]
	v_mfma_f32_16x16x32_bf16 v[46:49], v[154:157], v[190:193], v[46:49]
	v_mfma_f32_16x16x32_bf16 v[38:41], v[146:149], v[200:203], v[38:41]
	v_mfma_f32_16x16x32_bf16 v[30:33], v[154:157], v[200:203], v[30:33]
	v_mfma_f32_16x16x32_bf16 v[22:25], v[146:149], v[208:211], v[22:25]
	v_mfma_f32_16x16x32_bf16 v[14:17], v[154:157], v[208:211], v[14:17]
	v_mfma_f32_16x16x32_bf16 v[6:9], v[146:149], v[216:219], v[6:9]
	v_mfma_f32_16x16x32_bf16 v[2:5], v[154:157], v[216:219], v[2:5]
	v_mfma_f32_16x16x32_bf16 v[54:57], v[150:153], v[196:199], v[54:57]
	v_mfma_f32_16x16x32_bf16 v[46:49], v[178:181], v[196:199], v[46:49]
	v_mfma_f32_16x16x32_bf16 v[38:41], v[150:153], v[204:207], v[38:41]
	v_mfma_f32_16x16x32_bf16 v[30:33], v[178:181], v[204:207], v[30:33]
	v_mfma_f32_16x16x32_bf16 v[22:25], v[150:153], v[212:215], v[22:25]
	v_mfma_f32_16x16x32_bf16 v[14:17], v[178:181], v[212:215], v[14:17]
	v_mfma_f32_16x16x32_bf16 v[6:9], v[150:153], v[220:223], v[6:9]
	v_mfma_f32_16x16x32_bf16 v[2:5], v[178:181], v[220:223], v[2:5]
	s_setprio 0
	s_barrier
	s_add_i32 s46, s46, 2
	s_add_u32 s20, s20, 0x100
	s_addc_u32 s21, s21, 0
	s_cmp_gt_u32 s46, 13
	s_cbranch_scc1 .LBB0_584

.LBB0_671:
	ds_read_b128 v[132:135], v222
	ds_read_b128 v[136:139], v222 offset:1024
	ds_read_b128 v[140:143], v222 offset:2048
	ds_read_b128 v[144:147], v222 offset:3072
	ds_read_b128 v[148:151], v223
	ds_read_b128 v[152:155], v223 offset:1024
	ds_read_b128 v[156:159], v223 offset:2048
	ds_read_b128 v[160:163], v223 offset:3072
	s_add_u32 s10, s8, 0xfffc0080
	s_addc_u32 s11, s9, -1
	s_cmp_eq_u32 s58, 12
	s_cselect_b32 s27, s5, s11
	s_cselect_b32 s26, s7, s10
	s_cselect_b32 s11, s19, s57
	s_cselect_b32 s10, s21, s56
	v_lshl_add_u64 v[192:193], s[8:9], 0, v[204:205]
	s_add_i32 m0, s30, 0xc000
	ds_read_b128 v[164:167], v224
	ds_read_b128 v[168:171], v224 offset:1024
	ds_read_b128 v[172:175], v224 offset:2048
	ds_read_b128 v[176:179], v224 offset:3072
	ds_read_b128 v[180:183], v224 offset:4096
	ds_read_b128 v[184:187], v224 offset:5120
	ds_read_b128 v[188:191], v224 offset:6144
	ds_read_b128 v[208:211], v224 offset:7168
	global_load_lds_dwordx4 v[192:193], off
	v_lshl_add_u64 v[192:193], s[8:9], 0, v[206:207]
	s_add_i32 m0, s30, 0xe000
	s_nop 0
	global_load_lds_dwordx4 v[192:193], off
	s_waitcnt lgkmcnt(0)
	v_mfma_f32_16x16x32_bf16 v[126:129], v[132:135], v[164:167], v[126:129]
	v_mfma_f32_16x16x32_bf16 v[122:125], v[140:143], v[164:167], v[122:125]
	v_mfma_f32_16x16x32_bf16 v[110:113], v[132:135], v[172:175], v[110:113]
	v_mfma_f32_16x16x32_bf16 v[106:109], v[140:143], v[172:175], v[106:109]
	v_mfma_f32_16x16x32_bf16 v[94:97], v[132:135], v[180:183], v[94:97]
	v_mfma_f32_16x16x32_bf16 v[90:93], v[140:143], v[180:183], v[90:93]
	v_mfma_f32_16x16x32_bf16 v[78:81], v[132:135], v[188:191], v[78:81]
	v_mfma_f32_16x16x32_bf16 v[74:77], v[140:143], v[188:191], v[74:77]
	s_waitcnt vmcnt(8)
	s_waitcnt lgkmcnt(0)
	s_barrier
	s_setprio 1
	s_waitcnt lgkmcnt(0)
	v_mfma_f32_16x16x32_bf16 v[126:129], v[136:139], v[168:171], v[126:129]
	v_mfma_f32_16x16x32_bf16 v[122:125], v[144:147], v[168:171], v[122:125]
	v_mfma_f32_16x16x32_bf16 v[110:113], v[136:139], v[176:179], v[110:113]
	v_mfma_f32_16x16x32_bf16 v[106:109], v[144:147], v[176:179], v[106:109]
	v_mfma_f32_16x16x32_bf16 v[94:97], v[136:139], v[184:187], v[94:97]
	v_mfma_f32_16x16x32_bf16 v[90:93], v[144:147], v[184:187], v[90:93]
	v_mfma_f32_16x16x32_bf16 v[78:81], v[136:139], v[208:211], v[78:81]
	v_mfma_f32_16x16x32_bf16 v[74:77], v[144:147], v[208:211], v[74:77]
	s_setprio 0
	s_setprio 1
	v_mfma_f32_16x16x32_bf16 v[118:121], v[148:151], v[164:167], v[118:121]
	v_mfma_f32_16x16x32_bf16 v[114:117], v[156:159], v[164:167], v[114:117]
	v_mfma_f32_16x16x32_bf16 v[102:105], v[148:151], v[172:175], v[102:105]
	v_mfma_f32_16x16x32_bf16 v[98:101], v[156:159], v[172:175], v[98:101]
	v_mfma_f32_16x16x32_bf16 v[86:89], v[148:151], v[180:183], v[86:89]
	v_mfma_f32_16x16x32_bf16 v[82:85], v[156:159], v[180:183], v[82:85]
	v_mfma_f32_16x16x32_bf16 v[70:73], v[148:151], v[188:191], v[70:73]
	v_mfma_f32_16x16x32_bf16 v[66:69], v[156:159], v[188:191], v[66:69]
	v_mfma_f32_16x16x32_bf16 v[118:121], v[152:155], v[168:171], v[118:121]
	v_mfma_f32_16x16x32_bf16 v[114:117], v[160:163], v[168:171], v[114:117]
	v_mfma_f32_16x16x32_bf16 v[102:105], v[152:155], v[176:179], v[102:105]
	v_mfma_f32_16x16x32_bf16 v[98:101], v[160:163], v[176:179], v[98:101]
	v_mfma_f32_16x16x32_bf16 v[86:89], v[152:155], v[184:187], v[86:89]
	v_mfma_f32_16x16x32_bf16 v[82:85], v[160:163], v[184:187], v[82:85]
	v_mfma_f32_16x16x32_bf16 v[70:73], v[152:155], v[208:211], v[70:73]
	v_mfma_f32_16x16x32_bf16 v[66:69], v[160:163], v[208:211], v[66:69]
	s_setprio 0
	s_barrier
	s_add_i32 s59, s42, s29
	v_lshl_add_u64 v[192:193], s[10:11], 0, v[198:199]
	s_mov_b32 m0, s59
	ds_read_b128 v[164:167], v224 offset:16384
	ds_read_b128 v[168:171], v224 offset:17408
	ds_read_b128 v[172:175], v224 offset:18432
	ds_read_b128 v[176:179], v224 offset:19456
	ds_read_b128 v[180:183], v224 offset:20480
	ds_read_b128 v[184:187], v224 offset:21504
	ds_read_b128 v[188:191], v224 offset:22528
	ds_read_b128 v[208:211], v224 offset:23552
	global_load_lds_dwordx4 v[192:193], off
	s_add_i32 m0, s59, 0x2000
	s_add_u32 s60, s10, 0x40000
	v_lshl_add_u64 v[212:213], s[10:11], 0, v[202:203]
	s_addc_u32 s61, s11, 0
	s_add_i32 s59, s43, s29
	global_load_lds_dwordx4 v[212:213], off
	v_lshl_add_u64 v[214:215], s[60:61], 0, v[198:199]
	s_mov_b32 m0, s59
	v_lshl_add_u64 v[216:217], s[26:27], 0, v[200:201]
	global_load_lds_dwordx4 v[214:215], off
	v_lshl_add_u64 v[214:215], s[60:61], 0, v[202:203]
	s_add_i32 m0, s59, 0x2000
	s_nop 0
	global_load_lds_dwordx4 v[214:215], off
	v_lshl_add_u64 v[214:215], s[26:27], 0, v[196:197]
	s_mov_b32 m0, s30
	s_nop 0
	global_load_lds_dwordx4 v[214:215], off
	s_mov_b32 m0, s31
	s_nop 0
	global_load_lds_dwordx4 v[216:217], off
	s_waitcnt lgkmcnt(0)
	v_mfma_f32_16x16x32_bf16 v[62:65], v[132:135], v[164:167], v[62:65]
	v_mfma_f32_16x16x32_bf16 v[58:61], v[140:143], v[164:167], v[58:61]
	v_mfma_f32_16x16x32_bf16 v[46:49], v[132:135], v[172:175], v[46:49]
	v_mfma_f32_16x16x32_bf16 v[42:45], v[140:143], v[172:175], v[42:45]
	v_mfma_f32_16x16x32_bf16 v[30:33], v[132:135], v[180:183], v[30:33]
	v_mfma_f32_16x16x32_bf16 v[26:29], v[140:143], v[180:183], v[26:29]
	v_mfma_f32_16x16x32_bf16 v[14:17], v[132:135], v[188:191], v[14:17]
	v_mfma_f32_16x16x32_bf16 v[10:13], v[140:143], v[188:191], v[10:13]
	s_waitcnt vmcnt(8)
	s_waitcnt lgkmcnt(0)
	s_barrier
	s_setprio 1
	s_waitcnt lgkmcnt(0)
	v_mfma_f32_16x16x32_bf16 v[62:65], v[136:139], v[168:171], v[62:65]
	v_mfma_f32_16x16x32_bf16 v[58:61], v[144:147], v[168:171], v[58:61]
	v_mfma_f32_16x16x32_bf16 v[46:49], v[136:139], v[176:179], v[46:49]
	v_mfma_f32_16x16x32_bf16 v[42:45], v[144:147], v[176:179], v[42:45]
	v_mfma_f32_16x16x32_bf16 v[30:33], v[136:139], v[184:187], v[30:33]
	v_mfma_f32_16x16x32_bf16 v[26:29], v[144:147], v[184:187], v[26:29]
	v_mfma_f32_16x16x32_bf16 v[14:17], v[136:139], v[208:211], v[14:17]
	v_mfma_f32_16x16x32_bf16 v[10:13], v[144:147], v[208:211], v[10:13]
	s_setprio 0
	s_setprio 1
	v_mfma_f32_16x16x32_bf16 v[54:57], v[148:151], v[164:167], v[54:57]
	v_mfma_f32_16x16x32_bf16 v[50:53], v[156:159], v[164:167], v[50:53]
	v_mfma_f32_16x16x32_bf16 v[38:41], v[148:151], v[172:175], v[38:41]
	v_mfma_f32_16x16x32_bf16 v[34:37], v[156:159], v[172:175], v[34:37]
	v_mfma_f32_16x16x32_bf16 v[22:25], v[148:151], v[180:183], v[22:25]
	v_mfma_f32_16x16x32_bf16 v[18:21], v[156:159], v[180:183], v[18:21]
	v_mfma_f32_16x16x32_bf16 v[6:9], v[148:151], v[188:191], v[6:9]
	v_mfma_f32_16x16x32_bf16 v[2:5], v[156:159], v[188:191], v[2:5]
	v_mfma_f32_16x16x32_bf16 v[54:57], v[152:155], v[168:171], v[54:57]
	v_mfma_f32_16x16x32_bf16 v[50:53], v[160:163], v[168:171], v[50:53]
	v_mfma_f32_16x16x32_bf16 v[38:41], v[152:155], v[176:179], v[38:41]
	v_mfma_f32_16x16x32_bf16 v[34:37], v[160:163], v[176:179], v[34:37]
	v_mfma_f32_16x16x32_bf16 v[22:25], v[152:155], v[184:187], v[22:25]
	v_mfma_f32_16x16x32_bf16 v[18:21], v[160:163], v[184:187], v[18:21]
	v_mfma_f32_16x16x32_bf16 v[6:9], v[152:155], v[208:211], v[6:9]
	v_mfma_f32_16x16x32_bf16 v[2:5], v[160:163], v[208:211], v[2:5]
	s_setprio 0
	s_barrier
	s_add_i32 s59, 0, 0x18000
	v_add_u32_e32 v131, s59, v220
	s_add_i32 s60, 0, 0x1c000
	ds_read_b128 v[132:135], v131
	ds_read_b128 v[136:139], v131 offset:1024
	ds_read_b128 v[140:143], v131 offset:2048
	ds_read_b128 v[144:147], v131 offset:3072
	v_add_u32_e32 v131, s60, v220
	ds_read_b128 v[148:151], v131
	ds_read_b128 v[152:155], v131 offset:1024
	ds_read_b128 v[156:159], v131 offset:2048
	ds_read_b128 v[160:163], v131 offset:3072
	s_add_u32 s26, s26, 0x40000
	s_addc_u32 s27, s27, 0
	s_mov_b32 m0, s34
	v_lshl_add_u64 v[218:219], s[26:27], 0, v[196:197]
	ds_read_b128 v[164:167], v224 offset:32768
	ds_read_b128 v[168:171], v224 offset:33792
	ds_read_b128 v[172:175], v224 offset:34816
	ds_read_b128 v[176:179], v224 offset:35840
	ds_read_b128 v[180:183], v224 offset:36864
	ds_read_b128 v[184:187], v224 offset:37888
	ds_read_b128 v[188:191], v224 offset:38912
	ds_read_b128 v[208:211], v224 offset:39936
	global_load_lds_dwordx4 v[218:219], off
	v_lshl_add_u64 v[218:219], s[26:27], 0, v[200:201]
	s_mov_b32 m0, s35
	s_nop 0
	global_load_lds_dwordx4 v[218:219], off
	s_waitcnt lgkmcnt(0)
	v_mfma_f32_16x16x32_bf16 v[126:129], v[132:135], v[164:167], v[126:129]
	v_mfma_f32_16x16x32_bf16 v[122:125], v[140:143], v[164:167], v[122:125]
	v_mfma_f32_16x16x32_bf16 v[110:113], v[132:135], v[172:175], v[110:113]
	v_mfma_f32_16x16x32_bf16 v[106:109], v[140:143], v[172:175], v[106:109]
	v_mfma_f32_16x16x32_bf16 v[94:97], v[132:135], v[180:183], v[94:97]
	v_mfma_f32_16x16x32_bf16 v[90:93], v[140:143], v[180:183], v[90:93]
	v_mfma_f32_16x16x32_bf16 v[78:81], v[132:135], v[188:191], v[78:81]
	v_mfma_f32_16x16x32_bf16 v[74:77], v[140:143], v[188:191], v[74:77]
	s_waitcnt vmcnt(8)
	s_waitcnt lgkmcnt(0)
	s_barrier
	s_setprio 1
	s_waitcnt lgkmcnt(0)
	v_mfma_f32_16x16x32_bf16 v[126:129], v[136:139], v[168:171], v[126:129]
	v_mfma_f32_16x16x32_bf16 v[122:125], v[144:147], v[168:171], v[122:125]
	v_mfma_f32_16x16x32_bf16 v[110:113], v[136:139], v[176:179], v[110:113]
	v_mfma_f32_16x16x32_bf16 v[106:109], v[144:147], v[176:179], v[106:109]
	v_mfma_f32_16x16x32_bf16 v[94:97], v[136:139], v[184:187], v[94:97]
	v_mfma_f32_16x16x32_bf16 v[90:93], v[144:147], v[184:187], v[90:93]
	v_mfma_f32_16x16x32_bf16 v[78:81], v[136:139], v[208:211], v[78:81]
	v_mfma_f32_16x16x32_bf16 v[74:77], v[144:147], v[208:211], v[74:77]
	s_setprio 0
	s_setprio 1
	v_mfma_f32_16x16x32_bf16 v[118:121], v[148:151], v[164:167], v[118:121]
	v_mfma_f32_16x16x32_bf16 v[114:117], v[156:159], v[164:167], v[114:117]
	v_mfma_f32_16x16x32_bf16 v[102:105], v[148:151], v[172:175], v[102:105]
	v_mfma_f32_16x16x32_bf16 v[98:101], v[156:159], v[172:175], v[98:101]
	v_mfma_f32_16x16x32_bf16 v[86:89], v[148:151], v[180:183], v[86:89]
	v_mfma_f32_16x16x32_bf16 v[82:85], v[156:159], v[180:183], v[82:85]
	v_mfma_f32_16x16x32_bf16 v[70:73], v[148:151], v[188:191], v[70:73]
	v_mfma_f32_16x16x32_bf16 v[66:69], v[156:159], v[188:191], v[66:69]
	v_mfma_f32_16x16x32_bf16 v[118:121], v[152:155], v[168:171], v[118:121]
	v_mfma_f32_16x16x32_bf16 v[114:117], v[160:163], v[168:171], v[114:117]
	v_mfma_f32_16x16x32_bf16 v[102:105], v[152:155], v[176:179], v[102:105]
	v_mfma_f32_16x16x32_bf16 v[98:101], v[160:163], v[176:179], v[98:101]
	v_mfma_f32_16x16x32_bf16 v[86:89], v[152:155], v[184:187], v[86:89]
	v_mfma_f32_16x16x32_bf16 v[82:85], v[160:163], v[184:187], v[82:85]
	v_mfma_f32_16x16x32_bf16 v[70:73], v[152:155], v[208:211], v[70:73]
	v_mfma_f32_16x16x32_bf16 v[66:69], v[160:163], v[208:211], v[66:69]
	s_setprio 0
	s_barrier
	s_add_i32 s26, s59, s29
	v_lshl_add_u64 v[192:193], v[192:193], 0, s[14:15]
	s_mov_b32 m0, s26
	ds_read_b128 v[164:167], v224 offset:49152
	ds_read_b128 v[168:171], v224 offset:50176
	ds_read_b128 v[172:175], v224 offset:51200
	ds_read_b128 v[176:179], v224 offset:52224
	ds_read_b128 v[180:183], v224 offset:53248
	ds_read_b128 v[184:187], v224 offset:54272
	ds_read_b128 v[188:191], v224 offset:55296
	ds_read_b128 v[208:211], v224 offset:56320
	global_load_lds_dwordx4 v[192:193], off
	s_add_i32 m0, s26, 0x2000
	s_add_u32 s10, s10, 0x40080
	v_lshl_add_u64 v[192:193], v[212:213], 0, s[14:15]
	s_addc_u32 s11, s11, 0
	s_add_i32 s26, s60, s29
	global_load_lds_dwordx4 v[192:193], off
	v_lshl_add_u64 v[192:193], s[10:11], 0, v[198:199]
	s_mov_b32 m0, s26
	s_nop 0
	global_load_lds_dwordx4 v[192:193], off
	v_lshl_add_u64 v[192:193], s[10:11], 0, v[202:203]
	s_add_i32 m0, s26, 0x2000
	s_nop 0
	global_load_lds_dwordx4 v[192:193], off
	v_lshl_add_u64 v[192:193], v[214:215], 0, s[14:15]
	s_mov_b32 m0, s38
	s_nop 0
	global_load_lds_dwordx4 v[192:193], off
	v_lshl_add_u64 v[192:193], v[216:217], 0, s[14:15]
	s_mov_b32 m0, s39
	s_nop 0
	global_load_lds_dwordx4 v[192:193], off
	s_waitcnt lgkmcnt(0)
	v_mfma_f32_16x16x32_bf16 v[62:65], v[132:135], v[164:167], v[62:65]
	v_mfma_f32_16x16x32_bf16 v[58:61], v[140:143], v[164:167], v[58:61]
	v_mfma_f32_16x16x32_bf16 v[46:49], v[132:135], v[172:175], v[46:49]
	v_mfma_f32_16x16x32_bf16 v[42:45], v[140:143], v[172:175], v[42:45]
	v_mfma_f32_16x16x32_bf16 v[30:33], v[132:135], v[180:183], v[30:33]
	v_mfma_f32_16x16x32_bf16 v[26:29], v[140:143], v[180:183], v[26:29]
	v_mfma_f32_16x16x32_bf16 v[14:17], v[132:135], v[188:191], v[14:17]
	v_mfma_f32_16x16x32_bf16 v[10:13], v[140:143], v[188:191], v[10:13]
	s_waitcnt vmcnt(8)
	s_waitcnt lgkmcnt(0)
	s_barrier
	s_setprio 1
	s_waitcnt lgkmcnt(0)
	v_mfma_f32_16x16x32_bf16 v[62:65], v[136:139], v[168:171], v[62:65]
	v_mfma_f32_16x16x32_bf16 v[58:61], v[144:147], v[168:171], v[58:61]
	v_mfma_f32_16x16x32_bf16 v[46:49], v[136:139], v[176:179], v[46:49]
	v_mfma_f32_16x16x32_bf16 v[42:45], v[144:147], v[176:179], v[42:45]
	v_mfma_f32_16x16x32_bf16 v[30:33], v[136:139], v[184:187], v[30:33]
	v_mfma_f32_16x16x32_bf16 v[26:29], v[144:147], v[184:187], v[26:29]
	v_mfma_f32_16x16x32_bf16 v[14:17], v[136:139], v[208:211], v[14:17]
	v_mfma_f32_16x16x32_bf16 v[10:13], v[144:147], v[208:211], v[10:13]
	s_setprio 0
	s_setprio 1
	v_mfma_f32_16x16x32_bf16 v[54:57], v[148:151], v[164:167], v[54:57]
	v_mfma_f32_16x16x32_bf16 v[50:53], v[156:159], v[164:167], v[50:53]
	v_mfma_f32_16x16x32_bf16 v[38:41], v[148:151], v[172:175], v[38:41]
	v_mfma_f32_16x16x32_bf16 v[34:37], v[156:159], v[172:175], v[34:37]
	v_mfma_f32_16x16x32_bf16 v[22:25], v[148:151], v[180:183], v[22:25]
	v_mfma_f32_16x16x32_bf16 v[18:21], v[156:159], v[180:183], v[18:21]
	v_mfma_f32_16x16x32_bf16 v[6:9], v[148:151], v[188:191], v[6:9]
	v_mfma_f32_16x16x32_bf16 v[2:5], v[156:159], v[188:191], v[2:5]
	v_mfma_f32_16x16x32_bf16 v[54:57], v[152:155], v[168:171], v[54:57]
	v_mfma_f32_16x16x32_bf16 v[50:53], v[160:163], v[168:171], v[50:53]
	v_mfma_f32_16x16x32_bf16 v[38:41], v[152:155], v[176:179], v[38:41]
	v_mfma_f32_16x16x32_bf16 v[34:37], v[160:163], v[176:179], v[34:37]
	v_mfma_f32_16x16x32_bf16 v[22:25], v[152:155], v[184:187], v[22:25]
	v_mfma_f32_16x16x32_bf16 v[18:21], v[160:163], v[184:187], v[18:21]
	v_mfma_f32_16x16x32_bf16 v[6:9], v[152:155], v[208:211], v[6:9]
	v_mfma_f32_16x16x32_bf16 v[2:5], v[160:163], v[208:211], v[2:5]
	s_setprio 0
	s_barrier
	s_add_i32 s58, s58, 2
	s_add_u32 s8, s8, 0x100
	s_addc_u32 s9, s9, 0
	s_add_u32 s56, s56, 0x100
	s_addc_u32 s57, s57, 0
	s_cmp_gt_u32 s58, 13
	s_cbranch_scc0 .LBB0_671
	s_and_b64 vcc, exec, s[16:17]
	s_cbranch_vccz .LBB0_674
	s_barrier

.LBB0_841:
	ds_read_b128 v[148:151], v144
	ds_read_b128 v[152:155], v144 offset:1024
	ds_read_b128 v[156:159], v144 offset:2048
	ds_read_b128 v[160:163], v144 offset:3072
	ds_read_b128 v[164:167], v145
	ds_read_b128 v[168:171], v145 offset:1024
	ds_read_b128 v[172:175], v145 offset:2048
	ds_read_b128 v[176:179], v145 offset:3072
	s_add_u32 s22, s20, 0xfffc0080
	s_addc_u32 s23, s21, -1
	s_cmp_eq_u32 s45, 12
	s_cselect_b32 s25, s11, s23
	s_cselect_b32 s24, s41, s22
	s_cselect_b32 s23, s9, s44
	s_cselect_b32 s22, s42, s43
	v_lshl_add_u64 v[192:193], s[20:21], 0, v[138:139]
	s_add_i32 m0, s19, 0xc000
	ds_read_b128 v[180:183], v146
	ds_read_b128 v[184:187], v146 offset:1024
	ds_read_b128 v[188:191], v146 offset:2048
	ds_read_b128 v[196:199], v146 offset:3072
	ds_read_b128 v[200:203], v146 offset:4096
	ds_read_b128 v[204:207], v146 offset:5120
	ds_read_b128 v[208:211], v146 offset:6144
	ds_read_b128 v[212:215], v146 offset:7168
	global_load_lds_dwordx4 v[192:193], off
	v_lshl_add_u64 v[192:193], s[20:21], 0, v[140:141]
	s_add_i32 m0, s19, 0xe000
	s_nop 0
	global_load_lds_dwordx4 v[192:193], off
	s_waitcnt lgkmcnt(0)
	v_mfma_f32_16x16x32_bf16 v[126:129], v[148:151], v[180:183], v[126:129]
	v_mfma_f32_16x16x32_bf16 v[122:125], v[156:159], v[180:183], v[122:125]
	v_mfma_f32_16x16x32_bf16 v[110:113], v[148:151], v[188:191], v[110:113]
	v_mfma_f32_16x16x32_bf16 v[102:105], v[156:159], v[188:191], v[102:105]
	v_mfma_f32_16x16x32_bf16 v[94:97], v[148:151], v[200:203], v[94:97]
	v_mfma_f32_16x16x32_bf16 v[86:89], v[156:159], v[200:203], v[86:89]
	v_mfma_f32_16x16x32_bf16 v[78:81], v[148:151], v[208:211], v[78:81]
	v_mfma_f32_16x16x32_bf16 v[70:73], v[156:159], v[208:211], v[70:73]
	s_waitcnt vmcnt(8)
	s_waitcnt lgkmcnt(0)
	s_barrier
	s_setprio 1
	s_waitcnt lgkmcnt(0)
	v_mfma_f32_16x16x32_bf16 v[126:129], v[152:155], v[184:187], v[126:129]
	v_mfma_f32_16x16x32_bf16 v[122:125], v[160:163], v[184:187], v[122:125]
	v_mfma_f32_16x16x32_bf16 v[110:113], v[152:155], v[196:199], v[110:113]
	v_mfma_f32_16x16x32_bf16 v[102:105], v[160:163], v[196:199], v[102:105]
	v_mfma_f32_16x16x32_bf16 v[94:97], v[152:155], v[204:207], v[94:97]
	v_mfma_f32_16x16x32_bf16 v[86:89], v[160:163], v[204:207], v[86:89]
	v_mfma_f32_16x16x32_bf16 v[78:81], v[152:155], v[212:215], v[78:81]
	v_mfma_f32_16x16x32_bf16 v[70:73], v[160:163], v[212:215], v[70:73]
	s_setprio 0
	s_setprio 1
	v_mfma_f32_16x16x32_bf16 v[118:121], v[164:167], v[180:183], v[118:121]
	v_mfma_f32_16x16x32_bf16 v[114:117], v[172:175], v[180:183], v[114:117]
	v_mfma_f32_16x16x32_bf16 v[106:109], v[164:167], v[188:191], v[106:109]
	v_mfma_f32_16x16x32_bf16 v[98:101], v[172:175], v[188:191], v[98:101]
	v_mfma_f32_16x16x32_bf16 v[90:93], v[164:167], v[200:203], v[90:93]
	v_mfma_f32_16x16x32_bf16 v[82:85], v[172:175], v[200:203], v[82:85]
	v_mfma_f32_16x16x32_bf16 v[74:77], v[164:167], v[208:211], v[74:77]
	v_mfma_f32_16x16x32_bf16 v[66:69], v[172:175], v[208:211], v[66:69]
	v_mfma_f32_16x16x32_bf16 v[118:121], v[168:171], v[184:187], v[118:121]
	v_mfma_f32_16x16x32_bf16 v[114:117], v[176:179], v[184:187], v[114:117]
	v_mfma_f32_16x16x32_bf16 v[106:109], v[168:171], v[196:199], v[106:109]
	v_mfma_f32_16x16x32_bf16 v[98:101], v[176:179], v[196:199], v[98:101]
	v_mfma_f32_16x16x32_bf16 v[90:93], v[168:171], v[204:207], v[90:93]
	v_mfma_f32_16x16x32_bf16 v[82:85], v[176:179], v[204:207], v[82:85]
	v_mfma_f32_16x16x32_bf16 v[74:77], v[168:171], v[212:215], v[74:77]
	v_mfma_f32_16x16x32_bf16 v[66:69], v[176:179], v[212:215], v[66:69]
	s_setprio 0
	s_barrier
	s_add_i32 s46, s37, s27
	v_lshl_add_u64 v[192:193], s[22:23], 0, v[132:133]
	s_mov_b32 m0, s46
	ds_read_b128 v[180:183], v146 offset:16384
	ds_read_b128 v[184:187], v146 offset:17408
	ds_read_b128 v[188:191], v146 offset:18432
	ds_read_b128 v[196:199], v146 offset:19456
	ds_read_b128 v[200:203], v146 offset:20480
	ds_read_b128 v[204:207], v146 offset:21504
	ds_read_b128 v[208:211], v146 offset:22528
	ds_read_b128 v[212:215], v146 offset:23552
	global_load_lds_dwordx4 v[192:193], off
	s_add_i32 m0, s46, 0x2000
	s_add_u32 s46, s22, 0x40000
	v_lshl_add_u64 v[216:217], s[22:23], 0, v[136:137]
	s_addc_u32 s47, s23, 0
	s_add_i32 s48, s38, s27
	global_load_lds_dwordx4 v[216:217], off
	v_lshl_add_u64 v[218:219], s[46:47], 0, v[132:133]
	s_mov_b32 m0, s48
	v_lshl_add_u64 v[220:221], s[24:25], 0, v[134:135]
	global_load_lds_dwordx4 v[218:219], off
	v_lshl_add_u64 v[218:219], s[46:47], 0, v[136:137]
	s_add_i32 m0, s48, 0x2000
	s_nop 0
	global_load_lds_dwordx4 v[218:219], off
	v_lshl_add_u64 v[218:219], s[24:25], 0, v[130:131]
	s_mov_b32 m0, s19
	s_nop 0
	global_load_lds_dwordx4 v[218:219], off
	s_mov_b32 m0, s28
	s_nop 0
	global_load_lds_dwordx4 v[220:221], off
	s_waitcnt lgkmcnt(0)
	v_mfma_f32_16x16x32_bf16 v[62:65], v[148:151], v[180:183], v[62:65]
	v_mfma_f32_16x16x32_bf16 v[54:57], v[156:159], v[180:183], v[54:57]
	v_mfma_f32_16x16x32_bf16 v[46:49], v[148:151], v[188:191], v[46:49]
	v_mfma_f32_16x16x32_bf16 v[38:41], v[156:159], v[188:191], v[38:41]
	v_mfma_f32_16x16x32_bf16 v[30:33], v[148:151], v[200:203], v[30:33]
	v_mfma_f32_16x16x32_bf16 v[22:25], v[156:159], v[200:203], v[22:25]
	v_mfma_f32_16x16x32_bf16 v[14:17], v[148:151], v[208:211], v[14:17]
	v_mfma_f32_16x16x32_bf16 v[6:9], v[156:159], v[208:211], v[6:9]
	s_waitcnt vmcnt(8)
	s_waitcnt lgkmcnt(0)
	s_barrier
	s_setprio 1
	s_waitcnt lgkmcnt(0)
	v_mfma_f32_16x16x32_bf16 v[62:65], v[152:155], v[184:187], v[62:65]
	v_mfma_f32_16x16x32_bf16 v[54:57], v[160:163], v[184:187], v[54:57]
	v_mfma_f32_16x16x32_bf16 v[46:49], v[152:155], v[196:199], v[46:49]
	v_mfma_f32_16x16x32_bf16 v[38:41], v[160:163], v[196:199], v[38:41]
	v_mfma_f32_16x16x32_bf16 v[30:33], v[152:155], v[204:207], v[30:33]
	v_mfma_f32_16x16x32_bf16 v[22:25], v[160:163], v[204:207], v[22:25]
	v_mfma_f32_16x16x32_bf16 v[14:17], v[152:155], v[212:215], v[14:17]
	v_mfma_f32_16x16x32_bf16 v[6:9], v[160:163], v[212:215], v[6:9]
	s_setprio 0
	s_setprio 1
	v_mfma_f32_16x16x32_bf16 v[58:61], v[164:167], v[180:183], v[58:61]
	v_mfma_f32_16x16x32_bf16 v[50:53], v[172:175], v[180:183], v[50:53]
	v_mfma_f32_16x16x32_bf16 v[42:45], v[164:167], v[188:191], v[42:45]
	v_mfma_f32_16x16x32_bf16 v[34:37], v[172:175], v[188:191], v[34:37]
	v_mfma_f32_16x16x32_bf16 v[26:29], v[164:167], v[200:203], v[26:29]
	v_mfma_f32_16x16x32_bf16 v[18:21], v[172:175], v[200:203], v[18:21]
	v_mfma_f32_16x16x32_bf16 v[10:13], v[164:167], v[208:211], v[10:13]
	v_mfma_f32_16x16x32_bf16 v[2:5], v[172:175], v[208:211], v[2:5]
	v_mfma_f32_16x16x32_bf16 v[58:61], v[168:171], v[184:187], v[58:61]
	v_mfma_f32_16x16x32_bf16 v[50:53], v[176:179], v[184:187], v[50:53]
	v_mfma_f32_16x16x32_bf16 v[42:45], v[168:171], v[196:199], v[42:45]
	v_mfma_f32_16x16x32_bf16 v[34:37], v[176:179], v[196:199], v[34:37]
	v_mfma_f32_16x16x32_bf16 v[26:29], v[168:171], v[204:207], v[26:29]
	v_mfma_f32_16x16x32_bf16 v[18:21], v[176:179], v[204:207], v[18:21]
	v_mfma_f32_16x16x32_bf16 v[10:13], v[168:171], v[212:215], v[10:13]
	v_mfma_f32_16x16x32_bf16 v[2:5], v[176:179], v[212:215], v[2:5]
	s_setprio 0
	s_barrier
	s_add_i32 s46, 0, 0x18000
	s_add_i32 s47, 0, 0x1c000
	v_add_u32_e32 v160, s46, v142
	v_add_u32_e32 v176, s47, v142
	ds_read_b128 v[148:151], v160
	ds_read_b128 v[152:155], v160 offset:1024
	ds_read_b128 v[156:159], v160 offset:2048
	ds_read_b128 v[160:163], v160 offset:3072
	ds_read_b128 v[164:167], v176
	ds_read_b128 v[168:171], v176 offset:1024
	ds_read_b128 v[172:175], v176 offset:2048
	ds_read_b128 v[176:179], v176 offset:3072
	s_add_u32 s24, s24, 0x40000
	s_addc_u32 s25, s25, 0
	s_mov_b32 m0, s29
	v_lshl_add_u64 v[222:223], s[24:25], 0, v[130:131]
	ds_read_b128 v[180:183], v146 offset:32768
	ds_read_b128 v[184:187], v146 offset:33792
	ds_read_b128 v[188:191], v146 offset:34816
	ds_read_b128 v[196:199], v146 offset:35840
	ds_read_b128 v[200:203], v146 offset:36864
	ds_read_b128 v[204:207], v146 offset:37888
	ds_read_b128 v[208:211], v146 offset:38912
	ds_read_b128 v[212:215], v146 offset:39936
	global_load_lds_dwordx4 v[222:223], off
	v_lshl_add_u64 v[222:223], s[24:25], 0, v[134:135]
	s_mov_b32 m0, s30
	s_nop 0
	global_load_lds_dwordx4 v[222:223], off
	s_waitcnt lgkmcnt(0)
	v_mfma_f32_16x16x32_bf16 v[126:129], v[148:151], v[180:183], v[126:129]
	v_mfma_f32_16x16x32_bf16 v[122:125], v[156:159], v[180:183], v[122:125]
	v_mfma_f32_16x16x32_bf16 v[110:113], v[148:151], v[188:191], v[110:113]
	v_mfma_f32_16x16x32_bf16 v[102:105], v[156:159], v[188:191], v[102:105]
	v_mfma_f32_16x16x32_bf16 v[94:97], v[148:151], v[200:203], v[94:97]
	v_mfma_f32_16x16x32_bf16 v[86:89], v[156:159], v[200:203], v[86:89]
	v_mfma_f32_16x16x32_bf16 v[78:81], v[148:151], v[208:211], v[78:81]
	v_mfma_f32_16x16x32_bf16 v[70:73], v[156:159], v[208:211], v[70:73]
	s_waitcnt vmcnt(8)
	s_waitcnt lgkmcnt(0)
	s_barrier
	s_setprio 1
	s_waitcnt lgkmcnt(0)
	v_mfma_f32_16x16x32_bf16 v[126:129], v[152:155], v[184:187], v[126:129]
	v_mfma_f32_16x16x32_bf16 v[122:125], v[160:163], v[184:187], v[122:125]
	v_mfma_f32_16x16x32_bf16 v[110:113], v[152:155], v[196:199], v[110:113]
	v_mfma_f32_16x16x32_bf16 v[102:105], v[160:163], v[196:199], v[102:105]
	v_mfma_f32_16x16x32_bf16 v[94:97], v[152:155], v[204:207], v[94:97]
	v_mfma_f32_16x16x32_bf16 v[86:89], v[160:163], v[204:207], v[86:89]
	v_mfma_f32_16x16x32_bf16 v[78:81], v[152:155], v[212:215], v[78:81]
	v_mfma_f32_16x16x32_bf16 v[70:73], v[160:163], v[212:215], v[70:73]
	s_setprio 0
	s_setprio 1
	v_mfma_f32_16x16x32_bf16 v[118:121], v[164:167], v[180:183], v[118:121]
	v_mfma_f32_16x16x32_bf16 v[114:117], v[172:175], v[180:183], v[114:117]
	v_mfma_f32_16x16x32_bf16 v[106:109], v[164:167], v[188:191], v[106:109]
	v_mfma_f32_16x16x32_bf16 v[98:101], v[172:175], v[188:191], v[98:101]
	v_mfma_f32_16x16x32_bf16 v[90:93], v[164:167], v[200:203], v[90:93]
	v_mfma_f32_16x16x32_bf16 v[82:85], v[172:175], v[200:203], v[82:85]
	v_mfma_f32_16x16x32_bf16 v[74:77], v[164:167], v[208:211], v[74:77]
	v_mfma_f32_16x16x32_bf16 v[66:69], v[172:175], v[208:211], v[66:69]
	v_mfma_f32_16x16x32_bf16 v[118:121], v[168:171], v[184:187], v[118:121]
	v_mfma_f32_16x16x32_bf16 v[114:117], v[176:179], v[184:187], v[114:117]
	v_mfma_f32_16x16x32_bf16 v[106:109], v[168:171], v[196:199], v[106:109]
	v_mfma_f32_16x16x32_bf16 v[98:101], v[176:179], v[196:199], v[98:101]
	v_mfma_f32_16x16x32_bf16 v[90:93], v[168:171], v[204:207], v[90:93]
	v_mfma_f32_16x16x32_bf16 v[82:85], v[176:179], v[204:207], v[82:85]
	v_mfma_f32_16x16x32_bf16 v[74:77], v[168:171], v[212:215], v[74:77]
	v_mfma_f32_16x16x32_bf16 v[66:69], v[176:179], v[212:215], v[66:69]
	s_setprio 0
	s_barrier
	s_add_i32 s24, s46, s27
	v_lshl_add_u64 v[192:193], v[192:193], 0, s[4:5]
	s_mov_b32 m0, s24
	ds_read_b128 v[180:183], v146 offset:49152
	ds_read_b128 v[184:187], v146 offset:50176
	ds_read_b128 v[188:191], v146 offset:51200
	ds_read_b128 v[196:199], v146 offset:52224
	ds_read_b128 v[200:203], v146 offset:53248
	ds_read_b128 v[204:207], v146 offset:54272
	ds_read_b128 v[208:211], v146 offset:55296
	ds_read_b128 v[212:215], v146 offset:56320
	global_load_lds_dwordx4 v[192:193], off
	s_add_i32 m0, s24, 0x2000
	s_add_u32 s22, s22, 0x40080
	v_lshl_add_u64 v[192:193], v[216:217], 0, s[4:5]
	s_addc_u32 s23, s23, 0
	s_add_i32 s24, s47, s27
	global_load_lds_dwordx4 v[192:193], off
	v_lshl_add_u64 v[192:193], s[22:23], 0, v[132:133]
	s_mov_b32 m0, s24
	s_nop 0
	global_load_lds_dwordx4 v[192:193], off
	v_lshl_add_u64 v[192:193], s[22:23], 0, v[136:137]
	s_add_i32 m0, s24, 0x2000
	s_nop 0
	global_load_lds_dwordx4 v[192:193], off
	v_lshl_add_u64 v[192:193], v[218:219], 0, s[4:5]
	s_mov_b32 m0, s31
	s_nop 0
	global_load_lds_dwordx4 v[192:193], off
	v_lshl_add_u64 v[192:193], v[220:221], 0, s[4:5]
	s_mov_b32 m0, s34
	s_nop 0
	global_load_lds_dwordx4 v[192:193], off
	s_waitcnt lgkmcnt(0)
	v_mfma_f32_16x16x32_bf16 v[62:65], v[148:151], v[180:183], v[62:65]
	v_mfma_f32_16x16x32_bf16 v[54:57], v[156:159], v[180:183], v[54:57]
	v_mfma_f32_16x16x32_bf16 v[46:49], v[148:151], v[188:191], v[46:49]
	v_mfma_f32_16x16x32_bf16 v[38:41], v[156:159], v[188:191], v[38:41]
	v_mfma_f32_16x16x32_bf16 v[30:33], v[148:151], v[200:203], v[30:33]
	v_mfma_f32_16x16x32_bf16 v[22:25], v[156:159], v[200:203], v[22:25]
	v_mfma_f32_16x16x32_bf16 v[14:17], v[148:151], v[208:211], v[14:17]
	v_mfma_f32_16x16x32_bf16 v[6:9], v[156:159], v[208:211], v[6:9]
	s_waitcnt vmcnt(8)
	s_waitcnt lgkmcnt(0)
	s_barrier
	s_setprio 1
	s_waitcnt lgkmcnt(0)
	v_mfma_f32_16x16x32_bf16 v[62:65], v[152:155], v[184:187], v[62:65]
	v_mfma_f32_16x16x32_bf16 v[54:57], v[160:163], v[184:187], v[54:57]
	v_mfma_f32_16x16x32_bf16 v[46:49], v[152:155], v[196:199], v[46:49]
	v_mfma_f32_16x16x32_bf16 v[38:41], v[160:163], v[196:199], v[38:41]
	v_mfma_f32_16x16x32_bf16 v[30:33], v[152:155], v[204:207], v[30:33]
	v_mfma_f32_16x16x32_bf16 v[22:25], v[160:163], v[204:207], v[22:25]
	v_mfma_f32_16x16x32_bf16 v[14:17], v[152:155], v[212:215], v[14:17]
	v_mfma_f32_16x16x32_bf16 v[6:9], v[160:163], v[212:215], v[6:9]
	s_setprio 0
	s_setprio 1
	v_mfma_f32_16x16x32_bf16 v[58:61], v[164:167], v[180:183], v[58:61]
	v_mfma_f32_16x16x32_bf16 v[50:53], v[172:175], v[180:183], v[50:53]
	v_mfma_f32_16x16x32_bf16 v[42:45], v[164:167], v[188:191], v[42:45]
	v_mfma_f32_16x16x32_bf16 v[34:37], v[172:175], v[188:191], v[34:37]
	v_mfma_f32_16x16x32_bf16 v[26:29], v[164:167], v[200:203], v[26:29]
	v_mfma_f32_16x16x32_bf16 v[18:21], v[172:175], v[200:203], v[18:21]
	v_mfma_f32_16x16x32_bf16 v[10:13], v[164:167], v[208:211], v[10:13]
	v_mfma_f32_16x16x32_bf16 v[2:5], v[172:175], v[208:211], v[2:5]
	v_mfma_f32_16x16x32_bf16 v[58:61], v[168:171], v[184:187], v[58:61]
	v_mfma_f32_16x16x32_bf16 v[50:53], v[176:179], v[184:187], v[50:53]
	v_mfma_f32_16x16x32_bf16 v[42:45], v[168:171], v[196:199], v[42:45]
	v_mfma_f32_16x16x32_bf16 v[34:37], v[176:179], v[196:199], v[34:37]
	v_mfma_f32_16x16x32_bf16 v[26:29], v[168:171], v[204:207], v[26:29]
	v_mfma_f32_16x16x32_bf16 v[18:21], v[176:179], v[204:207], v[18:21]
	v_mfma_f32_16x16x32_bf16 v[10:13], v[168:171], v[212:215], v[10:13]
	v_mfma_f32_16x16x32_bf16 v[2:5], v[176:179], v[212:215], v[2:5]
	s_setprio 0
	s_barrier
	s_add_i32 s45, s45, 2
	s_add_u32 s20, s20, 0x100
	s_addc_u32 s21, s21, 0
	s_add_u32 s43, s43, 0x100
	s_addc_u32 s44, s44, 0
	s_cmp_gt_u32 s45, 13
	s_cbranch_scc0 .LBB0_841
	s_and_b64 vcc, exec, s[6:7]
	s_cbranch_vccz .LBB0_844
	s_barrier

.LBB0_928:
	ds_read_b128 v[132:135], v222
	ds_read_b128 v[136:139], v222 offset:1024
	ds_read_b128 v[140:143], v222 offset:2048
	ds_read_b128 v[144:147], v222 offset:3072
	ds_read_b128 v[148:151], v223
	ds_read_b128 v[152:155], v223 offset:1024
	ds_read_b128 v[156:159], v223 offset:2048
	ds_read_b128 v[160:163], v223 offset:3072
	s_add_u32 s12, s10, 0xfff50080
	s_addc_u32 s13, s11, -1
	s_cmp_eq_u32 s46, 40
	s_cselect_b32 s15, s9, s13
	s_cselect_b32 s14, s8, s12
	s_cselect_b32 s13, s1, s45
	s_cselect_b32 s12, s0, s44
	v_lshl_add_u64 v[184:185], s[10:11], 0, v[196:197]
	s_add_i32 m0, s18, 0xc000
	ds_read_b128 v[164:167], v224
	ds_read_b128 v[168:171], v224 offset:1024
	ds_read_b128 v[172:175], v224 offset:2048
	ds_read_b128 v[176:179], v224 offset:3072
	ds_read_b128 v[180:183], v224 offset:4096
	ds_read_b128 v[200:203], v224 offset:5120
	ds_read_b128 v[204:207], v224 offset:6144
	ds_read_b128 v[208:211], v224 offset:7168
	global_load_lds_dwordx4 v[184:185], off
	v_lshl_add_u64 v[184:185], s[10:11], 0, v[198:199]
	s_add_i32 m0, s18, 0xe000
	s_nop 0
	global_load_lds_dwordx4 v[184:185], off
	s_waitcnt lgkmcnt(0)
	v_mfma_f32_16x16x32_bf16 v[126:129], v[132:135], v[164:167], v[126:129]
	v_mfma_f32_16x16x32_bf16 v[122:125], v[140:143], v[164:167], v[122:125]
	v_mfma_f32_16x16x32_bf16 v[110:113], v[132:135], v[172:175], v[110:113]
	v_mfma_f32_16x16x32_bf16 v[106:109], v[140:143], v[172:175], v[106:109]
	v_mfma_f32_16x16x32_bf16 v[94:97], v[132:135], v[180:183], v[94:97]
	v_mfma_f32_16x16x32_bf16 v[90:93], v[140:143], v[180:183], v[90:93]
	v_mfma_f32_16x16x32_bf16 v[78:81], v[132:135], v[204:207], v[78:81]
	v_mfma_f32_16x16x32_bf16 v[74:77], v[140:143], v[204:207], v[74:77]
	s_waitcnt vmcnt(8)
	s_waitcnt lgkmcnt(0)
	s_barrier
	s_setprio 1
	s_waitcnt lgkmcnt(0)
	v_mfma_f32_16x16x32_bf16 v[126:129], v[136:139], v[168:171], v[126:129]
	v_mfma_f32_16x16x32_bf16 v[122:125], v[144:147], v[168:171], v[122:125]
	v_mfma_f32_16x16x32_bf16 v[110:113], v[136:139], v[176:179], v[110:113]
	v_mfma_f32_16x16x32_bf16 v[106:109], v[144:147], v[176:179], v[106:109]
	v_mfma_f32_16x16x32_bf16 v[94:97], v[136:139], v[200:203], v[94:97]
	v_mfma_f32_16x16x32_bf16 v[90:93], v[144:147], v[200:203], v[90:93]
	v_mfma_f32_16x16x32_bf16 v[78:81], v[136:139], v[208:211], v[78:81]
	v_mfma_f32_16x16x32_bf16 v[74:77], v[144:147], v[208:211], v[74:77]
	s_setprio 0
	s_setprio 1
	v_mfma_f32_16x16x32_bf16 v[118:121], v[148:151], v[164:167], v[118:121]
	v_mfma_f32_16x16x32_bf16 v[114:117], v[156:159], v[164:167], v[114:117]
	v_mfma_f32_16x16x32_bf16 v[102:105], v[148:151], v[172:175], v[102:105]
	v_mfma_f32_16x16x32_bf16 v[98:101], v[156:159], v[172:175], v[98:101]
	v_mfma_f32_16x16x32_bf16 v[86:89], v[148:151], v[180:183], v[86:89]
	v_mfma_f32_16x16x32_bf16 v[82:85], v[156:159], v[180:183], v[82:85]
	v_mfma_f32_16x16x32_bf16 v[70:73], v[148:151], v[204:207], v[70:73]
	v_mfma_f32_16x16x32_bf16 v[66:69], v[156:159], v[204:207], v[66:69]
	v_mfma_f32_16x16x32_bf16 v[118:121], v[152:155], v[168:171], v[118:121]
	v_mfma_f32_16x16x32_bf16 v[114:117], v[160:163], v[168:171], v[114:117]
	v_mfma_f32_16x16x32_bf16 v[102:105], v[152:155], v[176:179], v[102:105]
	v_mfma_f32_16x16x32_bf16 v[98:101], v[160:163], v[176:179], v[98:101]
	v_mfma_f32_16x16x32_bf16 v[86:89], v[152:155], v[200:203], v[86:89]
	v_mfma_f32_16x16x32_bf16 v[82:85], v[160:163], v[200:203], v[82:85]
	v_mfma_f32_16x16x32_bf16 v[70:73], v[152:155], v[208:211], v[70:73]
	v_mfma_f32_16x16x32_bf16 v[66:69], v[160:163], v[208:211], v[66:69]
	s_setprio 0
	s_barrier
	s_add_i32 s47, s28, s17
	v_lshl_add_u64 v[184:185], s[12:13], 0, v[188:189]
	s_mov_b32 m0, s47
	ds_read_b128 v[164:167], v224 offset:16384
	ds_read_b128 v[168:171], v224 offset:17408
	ds_read_b128 v[172:175], v224 offset:18432
	ds_read_b128 v[176:179], v224 offset:19456
	ds_read_b128 v[180:183], v224 offset:20480
	ds_read_b128 v[200:203], v224 offset:21504
	ds_read_b128 v[204:207], v224 offset:22528
	ds_read_b128 v[208:211], v224 offset:23552
	global_load_lds_dwordx4 v[184:185], off
	s_add_i32 m0, s47, 0x2000
	s_add_u32 s48, s12, 0xb0000
	v_lshl_add_u64 v[212:213], s[12:13], 0, v[192:193]
	s_addc_u32 s49, s13, 0
	s_add_i32 s47, s29, s17
	global_load_lds_dwordx4 v[212:213], off
	v_lshl_add_u64 v[214:215], s[48:49], 0, v[188:189]
	s_mov_b32 m0, s47
	v_lshl_add_u64 v[216:217], s[14:15], 0, v[190:191]
	global_load_lds_dwordx4 v[214:215], off
	v_lshl_add_u64 v[214:215], s[48:49], 0, v[192:193]
	s_add_i32 m0, s47, 0x2000
	s_nop 0
	global_load_lds_dwordx4 v[214:215], off
	v_lshl_add_u64 v[214:215], s[14:15], 0, v[186:187]
	s_mov_b32 m0, s18
	s_nop 0
	global_load_lds_dwordx4 v[214:215], off
	s_mov_b32 m0, s19
	s_nop 0
	global_load_lds_dwordx4 v[216:217], off
	s_waitcnt lgkmcnt(0)
	v_mfma_f32_16x16x32_bf16 v[62:65], v[132:135], v[164:167], v[62:65]
	v_mfma_f32_16x16x32_bf16 v[58:61], v[140:143], v[164:167], v[58:61]
	v_mfma_f32_16x16x32_bf16 v[46:49], v[132:135], v[172:175], v[46:49]
	v_mfma_f32_16x16x32_bf16 v[42:45], v[140:143], v[172:175], v[42:45]
	v_mfma_f32_16x16x32_bf16 v[30:33], v[132:135], v[180:183], v[30:33]
	v_mfma_f32_16x16x32_bf16 v[26:29], v[140:143], v[180:183], v[26:29]
	v_mfma_f32_16x16x32_bf16 v[14:17], v[132:135], v[204:207], v[14:17]
	v_mfma_f32_16x16x32_bf16 v[10:13], v[140:143], v[204:207], v[10:13]
	s_waitcnt vmcnt(8)
	s_waitcnt lgkmcnt(0)
	s_barrier
	s_setprio 1
	s_waitcnt lgkmcnt(0)
	v_mfma_f32_16x16x32_bf16 v[62:65], v[136:139], v[168:171], v[62:65]
	v_mfma_f32_16x16x32_bf16 v[58:61], v[144:147], v[168:171], v[58:61]
	v_mfma_f32_16x16x32_bf16 v[46:49], v[136:139], v[176:179], v[46:49]
	v_mfma_f32_16x16x32_bf16 v[42:45], v[144:147], v[176:179], v[42:45]
	v_mfma_f32_16x16x32_bf16 v[30:33], v[136:139], v[200:203], v[30:33]
	v_mfma_f32_16x16x32_bf16 v[26:29], v[144:147], v[200:203], v[26:29]
	v_mfma_f32_16x16x32_bf16 v[14:17], v[136:139], v[208:211], v[14:17]
	v_mfma_f32_16x16x32_bf16 v[10:13], v[144:147], v[208:211], v[10:13]
	s_setprio 0
	s_setprio 1
	v_mfma_f32_16x16x32_bf16 v[54:57], v[148:151], v[164:167], v[54:57]
	v_mfma_f32_16x16x32_bf16 v[50:53], v[156:159], v[164:167], v[50:53]
	v_mfma_f32_16x16x32_bf16 v[38:41], v[148:151], v[172:175], v[38:41]
	v_mfma_f32_16x16x32_bf16 v[34:37], v[156:159], v[172:175], v[34:37]
	v_mfma_f32_16x16x32_bf16 v[22:25], v[148:151], v[180:183], v[22:25]
	v_mfma_f32_16x16x32_bf16 v[18:21], v[156:159], v[180:183], v[18:21]
	v_mfma_f32_16x16x32_bf16 v[6:9], v[148:151], v[204:207], v[6:9]
	v_mfma_f32_16x16x32_bf16 v[2:5], v[156:159], v[204:207], v[2:5]
	v_mfma_f32_16x16x32_bf16 v[54:57], v[152:155], v[168:171], v[54:57]
	v_mfma_f32_16x16x32_bf16 v[50:53], v[160:163], v[168:171], v[50:53]
	v_mfma_f32_16x16x32_bf16 v[38:41], v[152:155], v[176:179], v[38:41]
	v_mfma_f32_16x16x32_bf16 v[34:37], v[160:163], v[176:179], v[34:37]
	v_mfma_f32_16x16x32_bf16 v[22:25], v[152:155], v[200:203], v[22:25]
	v_mfma_f32_16x16x32_bf16 v[18:21], v[160:163], v[200:203], v[18:21]
	v_mfma_f32_16x16x32_bf16 v[6:9], v[152:155], v[208:211], v[6:9]
	v_mfma_f32_16x16x32_bf16 v[2:5], v[160:163], v[208:211], v[2:5]
	s_setprio 0
	s_barrier
	s_add_i32 s47, 0, 0x18000
	v_add_u32_e32 v131, s47, v220
	s_add_i32 s48, 0, 0x1c000
	ds_read_b128 v[132:135], v131
	ds_read_b128 v[136:139], v131 offset:1024
	ds_read_b128 v[140:143], v131 offset:2048
	ds_read_b128 v[144:147], v131 offset:3072
	v_add_u32_e32 v131, s48, v220
	ds_read_b128 v[148:151], v131
	ds_read_b128 v[152:155], v131 offset:1024
	ds_read_b128 v[156:159], v131 offset:2048
	ds_read_b128 v[160:163], v131 offset:3072
	s_add_u32 s14, s14, 0xb0000
	s_addc_u32 s15, s15, 0
	s_mov_b32 m0, s20
	v_lshl_add_u64 v[218:219], s[14:15], 0, v[186:187]
	ds_read_b128 v[164:167], v224 offset:32768
	ds_read_b128 v[168:171], v224 offset:33792
	ds_read_b128 v[172:175], v224 offset:34816
	ds_read_b128 v[176:179], v224 offset:35840
	ds_read_b128 v[180:183], v224 offset:36864
	ds_read_b128 v[200:203], v224 offset:37888
	ds_read_b128 v[204:207], v224 offset:38912
	ds_read_b128 v[208:211], v224 offset:39936
	global_load_lds_dwordx4 v[218:219], off
	v_lshl_add_u64 v[218:219], s[14:15], 0, v[190:191]
	s_mov_b32 m0, s21
	s_nop 0
	global_load_lds_dwordx4 v[218:219], off
	s_waitcnt lgkmcnt(0)
	v_mfma_f32_16x16x32_bf16 v[126:129], v[132:135], v[164:167], v[126:129]
	v_mfma_f32_16x16x32_bf16 v[122:125], v[140:143], v[164:167], v[122:125]
	v_mfma_f32_16x16x32_bf16 v[110:113], v[132:135], v[172:175], v[110:113]
	v_mfma_f32_16x16x32_bf16 v[106:109], v[140:143], v[172:175], v[106:109]
	v_mfma_f32_16x16x32_bf16 v[94:97], v[132:135], v[180:183], v[94:97]
	v_mfma_f32_16x16x32_bf16 v[90:93], v[140:143], v[180:183], v[90:93]
	v_mfma_f32_16x16x32_bf16 v[78:81], v[132:135], v[204:207], v[78:81]
	v_mfma_f32_16x16x32_bf16 v[74:77], v[140:143], v[204:207], v[74:77]
	s_waitcnt vmcnt(8)
	s_waitcnt lgkmcnt(0)
	s_barrier
	s_setprio 1
	s_waitcnt lgkmcnt(0)
	v_mfma_f32_16x16x32_bf16 v[126:129], v[136:139], v[168:171], v[126:129]
	v_mfma_f32_16x16x32_bf16 v[122:125], v[144:147], v[168:171], v[122:125]
	v_mfma_f32_16x16x32_bf16 v[110:113], v[136:139], v[176:179], v[110:113]
	v_mfma_f32_16x16x32_bf16 v[106:109], v[144:147], v[176:179], v[106:109]
	v_mfma_f32_16x16x32_bf16 v[94:97], v[136:139], v[200:203], v[94:97]
	v_mfma_f32_16x16x32_bf16 v[90:93], v[144:147], v[200:203], v[90:93]
	v_mfma_f32_16x16x32_bf16 v[78:81], v[136:139], v[208:211], v[78:81]
	v_mfma_f32_16x16x32_bf16 v[74:77], v[144:147], v[208:211], v[74:77]
	s_setprio 0
	s_setprio 1
	v_mfma_f32_16x16x32_bf16 v[118:121], v[148:151], v[164:167], v[118:121]
	v_mfma_f32_16x16x32_bf16 v[114:117], v[156:159], v[164:167], v[114:117]
	v_mfma_f32_16x16x32_bf16 v[102:105], v[148:151], v[172:175], v[102:105]
	v_mfma_f32_16x16x32_bf16 v[98:101], v[156:159], v[172:175], v[98:101]
	v_mfma_f32_16x16x32_bf16 v[86:89], v[148:151], v[180:183], v[86:89]
	v_mfma_f32_16x16x32_bf16 v[82:85], v[156:159], v[180:183], v[82:85]
	v_mfma_f32_16x16x32_bf16 v[70:73], v[148:151], v[204:207], v[70:73]
	v_mfma_f32_16x16x32_bf16 v[66:69], v[156:159], v[204:207], v[66:69]
	v_mfma_f32_16x16x32_bf16 v[118:121], v[152:155], v[168:171], v[118:121]
	v_mfma_f32_16x16x32_bf16 v[114:117], v[160:163], v[168:171], v[114:117]
	v_mfma_f32_16x16x32_bf16 v[102:105], v[152:155], v[176:179], v[102:105]
	v_mfma_f32_16x16x32_bf16 v[98:101], v[160:163], v[176:179], v[98:101]
	v_mfma_f32_16x16x32_bf16 v[86:89], v[152:155], v[200:203], v[86:89]
	v_mfma_f32_16x16x32_bf16 v[82:85], v[160:163], v[200:203], v[82:85]
	v_mfma_f32_16x16x32_bf16 v[70:73], v[152:155], v[208:211], v[70:73]
	v_mfma_f32_16x16x32_bf16 v[66:69], v[160:163], v[208:211], v[66:69]
	s_setprio 0
	s_barrier
	s_add_i32 s14, s47, s17
	v_lshl_add_u64 v[184:185], v[184:185], 0, s[4:5]
	s_mov_b32 m0, s14
	ds_read_b128 v[164:167], v224 offset:49152
	ds_read_b128 v[168:171], v224 offset:50176
	ds_read_b128 v[172:175], v224 offset:51200
	ds_read_b128 v[176:179], v224 offset:52224
	ds_read_b128 v[180:183], v224 offset:53248
	ds_read_b128 v[200:203], v224 offset:54272
	ds_read_b128 v[204:207], v224 offset:55296
	ds_read_b128 v[208:211], v224 offset:56320
	global_load_lds_dwordx4 v[184:185], off
	s_add_i32 m0, s14, 0x2000
	s_add_u32 s12, s12, 0xb0080
	v_lshl_add_u64 v[184:185], v[212:213], 0, s[4:5]
	s_addc_u32 s13, s13, 0
	s_add_i32 s14, s48, s17
	global_load_lds_dwordx4 v[184:185], off
	v_lshl_add_u64 v[184:185], s[12:13], 0, v[188:189]
	s_mov_b32 m0, s14
	s_nop 0
	global_load_lds_dwordx4 v[184:185], off
	v_lshl_add_u64 v[184:185], s[12:13], 0, v[192:193]
	s_add_i32 m0, s14, 0x2000
	s_nop 0
	global_load_lds_dwordx4 v[184:185], off
	v_lshl_add_u64 v[184:185], v[214:215], 0, s[4:5]
	s_mov_b32 m0, s24
	s_nop 0
	global_load_lds_dwordx4 v[184:185], off
	v_lshl_add_u64 v[184:185], v[216:217], 0, s[4:5]
	s_mov_b32 m0, s25
	s_nop 0
	global_load_lds_dwordx4 v[184:185], off
	s_waitcnt lgkmcnt(0)
	v_mfma_f32_16x16x32_bf16 v[62:65], v[132:135], v[164:167], v[62:65]
	v_mfma_f32_16x16x32_bf16 v[58:61], v[140:143], v[164:167], v[58:61]
	v_mfma_f32_16x16x32_bf16 v[46:49], v[132:135], v[172:175], v[46:49]
	v_mfma_f32_16x16x32_bf16 v[42:45], v[140:143], v[172:175], v[42:45]
	v_mfma_f32_16x16x32_bf16 v[30:33], v[132:135], v[180:183], v[30:33]
	v_mfma_f32_16x16x32_bf16 v[26:29], v[140:143], v[180:183], v[26:29]
	v_mfma_f32_16x16x32_bf16 v[14:17], v[132:135], v[204:207], v[14:17]
	v_mfma_f32_16x16x32_bf16 v[10:13], v[140:143], v[204:207], v[10:13]
	s_waitcnt vmcnt(8)
	s_waitcnt lgkmcnt(0)
	s_barrier
	s_setprio 1
	s_waitcnt lgkmcnt(0)
	v_mfma_f32_16x16x32_bf16 v[62:65], v[136:139], v[168:171], v[62:65]
	v_mfma_f32_16x16x32_bf16 v[58:61], v[144:147], v[168:171], v[58:61]
	v_mfma_f32_16x16x32_bf16 v[46:49], v[136:139], v[176:179], v[46:49]
	v_mfma_f32_16x16x32_bf16 v[42:45], v[144:147], v[176:179], v[42:45]
	v_mfma_f32_16x16x32_bf16 v[30:33], v[136:139], v[200:203], v[30:33]
	v_mfma_f32_16x16x32_bf16 v[26:29], v[144:147], v[200:203], v[26:29]
	v_mfma_f32_16x16x32_bf16 v[14:17], v[136:139], v[208:211], v[14:17]
	v_mfma_f32_16x16x32_bf16 v[10:13], v[144:147], v[208:211], v[10:13]
	s_setprio 0
	s_setprio 1
	v_mfma_f32_16x16x32_bf16 v[54:57], v[148:151], v[164:167], v[54:57]
	v_mfma_f32_16x16x32_bf16 v[50:53], v[156:159], v[164:167], v[50:53]
	v_mfma_f32_16x16x32_bf16 v[38:41], v[148:151], v[172:175], v[38:41]
	v_mfma_f32_16x16x32_bf16 v[34:37], v[156:159], v[172:175], v[34:37]
	v_mfma_f32_16x16x32_bf16 v[22:25], v[148:151], v[180:183], v[22:25]
	v_mfma_f32_16x16x32_bf16 v[18:21], v[156:159], v[180:183], v[18:21]
	v_mfma_f32_16x16x32_bf16 v[6:9], v[148:151], v[204:207], v[6:9]
	v_mfma_f32_16x16x32_bf16 v[2:5], v[156:159], v[204:207], v[2:5]
	v_mfma_f32_16x16x32_bf16 v[54:57], v[152:155], v[168:171], v[54:57]
	v_mfma_f32_16x16x32_bf16 v[50:53], v[160:163], v[168:171], v[50:53]
	v_mfma_f32_16x16x32_bf16 v[38:41], v[152:155], v[176:179], v[38:41]
	v_mfma_f32_16x16x32_bf16 v[34:37], v[160:163], v[176:179], v[34:37]
	v_mfma_f32_16x16x32_bf16 v[22:25], v[152:155], v[200:203], v[22:25]
	v_mfma_f32_16x16x32_bf16 v[18:21], v[160:163], v[200:203], v[18:21]
	v_mfma_f32_16x16x32_bf16 v[6:9], v[152:155], v[208:211], v[6:9]
	v_mfma_f32_16x16x32_bf16 v[2:5], v[160:163], v[208:211], v[2:5]
	s_setprio 0
	s_barrier
	s_add_i32 s46, s46, 2
	s_add_u32 s10, s10, 0x100
	s_addc_u32 s11, s11, 0
	s_add_u32 s44, s44, 0x100
	s_addc_u32 s45, s45, 0
	s_cmp_gt_u32 s46, 41
	s_cbranch_scc0 .LBB0_928
	s_and_b64 vcc, exec, s[6:7]
	s_cbranch_vccz .LBB0_931
	s_barrier
